# A loop softmax pipelined in 8-value chunks under PV MFMAs, C loop QK alternates the two score accumulators; B as before; epilogue loads hoisted
# speedup vs baseline: 1.0018x; 1.0018x over previous
; __device__ __forceinline__ void pv_pipe(f32x16* o, int vb, VF& f0, VF& f1, bf16x8 pa0, bf16x8 pa1, bf16x8 pa2, bf16x8 pa3) {
;   v_issue<1>(f1, vb); asm volatile("s_waitcnt lgkmcnt(8)" ::: "memory"); SBAR(); pv_mma(o[0], f0, pa0, pa1, pa2, pa3); SBAR();
;   v_issue<2>(f0, vb); asm volatile("s_waitcnt lgkmcnt(8)" ::: "memory"); SBAR(); pv_mma(o[1], f1, pa0, pa1, pa2, pa3); SBAR();
;   v_issue<3>(f1, vb); asm volatile("s_waitcnt lgkmcnt(8)" ::: "memory"); SBAR(); pv_mma(o[2], f0, pa0, pa1, pa2, pa3); SBAR();
;   asm volatile("s_waitcnt lgkmcnt(0)" ::: "memory"); SBAR(); pv_mma(o[3], f1, pa0, pa1, pa2, pa3);
; }
;     ...
;       if constexpr (DQK == 64 && ATT_KEARLY) {
;         bf16x8 ka[4], kq[4]; const char* Ks = K_lds + b * SHM_K;
; #pragma unroll
;         for (int d0 = 0; d0 < 4; ++d0) { const int cb = (d0 * 16 + hi * 8) * 2;
;           ka[d0] = *reinterpret_cast<const bf16x8*>(Ks + KSWZ(KP, r32, cb)); kq[d0] = *reinterpret_cast<const bf16x8*>(Ks + KSWZ(KP, 32 + r32, cb)); }
;         SBAR();
;         if constexpr (!(ATT_STAGE_LATE & 1)) { if (j + 1 < nt) { SWRITE(b ^ 1, 0); } if (j + 2 < nt) { SLOAD(0, (j + 2) * KVBLK); } SBAR(); }
;         pA0 = f32x16{}; pA1 = f32x16{};
; #pragma unroll
;         for (int d0 = 0; d0 < 4; ++d0) { pA0 = __builtin_amdgcn_mfma_f32_32x32x16_bf16(ka[d0], qr[d0], pA0, 0, 0, 0); pA1 = __builtin_amdgcn_mfma_f32_32x32x16_bf16(kq[d0], qr[d0], pA1, 0, 0, 0); }
;         SBAR();
;         if constexpr (ATT_STAGE_LATE & 1) { if (j + 1 < nt) { SWRITE(b ^ 1, 0); } if (j + 2 < nt) { SLOAD(0, (j + 2) * KVBLK); } SBAR(); }
;       } else {
;       constexpr bool LATE = (DQK == 128) ? ((ATT_STAGE_LATE & 2) != 0) : ((ATT_STAGE_LATE & 4) != 0);
;       if constexpr (!LATE) { if (j + 1 < nt) { SWRITE(b ^ 1, 0); } if (j + 2 < nt) { SLOAD(0, (j + 2) * KVBLK); } }
;       SBAR(); qkt<DQK>(pA0, pA1, K_lds + b * SHM_K, qr, r32, hi); SBAR();
;       if constexpr (LATE) { if (j + 1 < nt) { SWRITE(b ^ 1, 0); } if (j + 2 < nt) { SLOAD(0, (j + 2) * KVBLK); } SBAR(); }
;       }
;       const int vb = vb0 + b * SHM_V;
;       if constexpr (DQK != 192) {
;         VF f0, f1; v_issue<0>(f0, vb);
;         partialSM<FIXM>(pA0, pA1, m_reg, mnA, alA, C, thrS, kb0 + j * KVBLK, hi);
;         RESC(alA);
;         finishSM<FIXM>(pA0, pA1, alA, l_reg, pa0, pa1, pa2, pa3, kb0 + j * KVBLK, hi); SBAR();
;         pv_pipe(o, vb, f0, f1, pa0, pa1, pa2, pa3);
.LBB0_501:
	s_and_b32 s2, s0, 1
	v_lshl_add_u32 v72, s2, 13, v143
	v_add_u32_e32 v68, v72, v147
	v_add_u32_e32 v73, v72, v146
	v_add_u32_e32 v74, v72, v145
	v_add_u32_e32 v75, v72, v144
	v_lshl_add_u32 v186, s2, 14, v129
	s_waitcnt lgkmcnt(0)
	s_barrier
	ds_read_b128 v[64:67], v68
	ds_read_b128 v[148:151], v73
	ds_read_b128 v[156:159], v74
	ds_read_b128 v[164:167], v75
	ds_read_b128 v[68:71], v68 offset:4096
	ds_read_b128 v[152:155], v73 offset:4096
	ds_read_b128 v[160:163], v74 offset:4096
	ds_read_b128 v[172:175], v75 offset:4096
	s_waitcnt lgkmcnt(7)
	v_mfma_f32_32x32x16_bf16 v[80:95], v[64:67], v[112:115], 0
	s_waitcnt lgkmcnt(6)
	v_mfma_f32_32x32x16_bf16 v[80:95], v[148:151], v[108:111], v[80:95]
	s_waitcnt lgkmcnt(5)
	v_mfma_f32_32x32x16_bf16 v[80:95], v[156:159], v[104:107], v[80:95]
	s_waitcnt lgkmcnt(4)
	v_mfma_f32_32x32x16_bf16 v[80:95], v[164:167], v[100:103], v[80:95]
	s_waitcnt lgkmcnt(3)
	v_mfma_f32_32x32x16_bf16 v[64:79], v[68:71], v[112:115], 0
	ds_read_b64_tr_b16 v[148:149], v186 offset:0x0
	ds_read_b64_tr_b16 v[150:151], v186 offset:0x800
	s_xor_b32 s3, s2, 1
	s_lshl_b32 s6, s3, 14
	s_waitcnt lgkmcnt(4)
	v_mfma_f32_32x32x16_bf16 v[64:79], v[152:155], v[108:111], v[64:79]
	ds_read_b64_tr_b16 v[156:157], v186 offset:0x200
	ds_read_b64_tr_b16 v[158:159], v186 offset:0xa00
	s_nop 1
	s_waitcnt lgkmcnt(5)
	v_mfma_f32_32x32x16_bf16 v[64:79], v[160:163], v[104:107], v[64:79]
	ds_read_b64_tr_b16 v[164:165], v186 offset:0x400
	ds_read_b64_tr_b16 v[166:167], v186 offset:0xc00
	v_exp_f32_e32 v80, v80
	v_exp_f32_e32 v81, v81
	v_add_f32_e32 v187, 0, v80
	v_exp_f32_e32 v82, v82
	v_add_f32_e32 v187, v81, v187
	v_exp_f32_e32 v83, v83
	v_add_f32_e32 v187, v82, v187
	s_waitcnt lgkmcnt(6)
	v_mfma_f32_32x32x16_bf16 v[64:79], v[172:175], v[100:103], v[64:79]
	ds_read_b64_tr_b16 v[176:177], v186 offset:0x600
	ds_read_b64_tr_b16 v[178:179], v186 offset:0xe00
	v_exp_f32_e32 v84, v84
	v_add_f32_e32 v187, v83, v187
	v_exp_f32_e32 v85, v85
	v_add_f32_e32 v187, v84, v187
	v_exp_f32_e32 v86, v86
	v_add_f32_e32 v187, v85, v187
	v_exp_f32_e32 v87, v87
	ds_read_b64_tr_b16 v[152:153], v186 offset:0x1000
	ds_read_b64_tr_b16 v[154:155], v186 offset:0x1800
	v_add_f32_e32 v187, v86, v187
	s_nop 0
	v_add_f32_e32 v187, v87, v187
	v_cvt_pk_bf16_f32 v80, v80, v81
	ds_read_b64_tr_b16 v[160:161], v186 offset:0x1200
	ds_read_b64_tr_b16 v[162:163], v186 offset:0x1a00
	v_cvt_pk_bf16_f32 v81, v82, v83
	v_cvt_pk_bf16_f32 v82, v84, v85
	v_cvt_pk_bf16_f32 v83, v86, v87
	s_nop 1
	s_waitcnt lgkmcnt(10)
	v_mfma_f32_32x32x16_bf16 v[0:15], v[80:83], v[148:151], v[0:15]
	ds_read_b64_tr_b16 v[148:149], v186 offset:0x1400
	ds_read_b64_tr_b16 v[150:151], v186 offset:0x1c00
	v_exp_f32_e32 v88, v88
	v_exp_f32_e32 v89, v89
	v_add_f32_e32 v187, v88, v187
	v_exp_f32_e32 v90, v90
	v_add_f32_e32 v187, v89, v187
	s_waitcnt lgkmcnt(10)
	v_mfma_f32_32x32x16_bf16 v[16:31], v[80:83], v[156:159], v[16:31]
	ds_read_b64_tr_b16 v[156:157], v186 offset:0x1600
	ds_read_b64_tr_b16 v[158:159], v186 offset:0x1e00
	v_exp_f32_e32 v91, v91
	v_add_f32_e32 v187, v90, v187
	v_exp_f32_e32 v92, v92
	v_add_f32_e32 v187, v91, v187
	v_exp_f32_e32 v93, v93
	s_waitcnt lgkmcnt(10)
	v_mfma_f32_32x32x16_bf16 v[32:47], v[80:83], v[164:167], v[32:47]
	ds_read_b64_tr_b16 v[164:165], v186 offset:0x2000
	ds_read_b64_tr_b16 v[166:167], v186 offset:0x2800
	v_add_f32_e32 v187, v92, v187
	v_exp_f32_e32 v94, v94
	v_add_f32_e32 v187, v93, v187
	v_exp_f32_e32 v95, v95
	v_add_f32_e32 v187, v94, v187
	s_waitcnt lgkmcnt(10)
	v_mfma_f32_32x32x16_bf16 v[48:63], v[80:83], v[176:179], v[48:63]
	ds_read_b64_tr_b16 v[176:177], v186 offset:0x2200
	ds_read_b64_tr_b16 v[178:179], v186 offset:0x2a00
	s_nop 0
	v_add_f32_e32 v187, v95, v187
	v_cvt_pk_bf16_f32 v84, v88, v89
	v_cvt_pk_bf16_f32 v85, v90, v91
	v_cvt_pk_bf16_f32 v86, v92, v93
	v_cvt_pk_bf16_f32 v87, v94, v95
	s_nop 0
	s_waitcnt lgkmcnt(10)
	v_mfma_f32_32x32x16_bf16 v[0:15], v[84:87], v[152:155], v[0:15]
	ds_read_b64_tr_b16 v[152:153], v186 offset:0x2400
	ds_read_b64_tr_b16 v[154:155], v186 offset:0x2c00
	v_exp_f32_e32 v64, v64
	v_exp_f32_e32 v65, v65
	v_add_f32_e32 v187, v64, v187
	v_exp_f32_e32 v66, v66
	v_add_f32_e32 v187, v65, v187
	s_waitcnt lgkmcnt(10)
	v_mfma_f32_32x32x16_bf16 v[16:31], v[84:87], v[160:163], v[16:31]
	ds_read_b64_tr_b16 v[160:161], v186 offset:0x2600
	ds_read_b64_tr_b16 v[162:163], v186 offset:0x2e00
	v_exp_f32_e32 v67, v67
	v_add_f32_e32 v187, v66, v187
	v_exp_f32_e32 v68, v68
	v_add_f32_e32 v187, v67, v187
	v_exp_f32_e32 v69, v69
	s_waitcnt lgkmcnt(10)
	v_mfma_f32_32x32x16_bf16 v[32:47], v[84:87], v[148:151], v[32:47]
	ds_read_b64_tr_b16 v[148:149], v186 offset:0x3000
	ds_read_b64_tr_b16 v[150:151], v186 offset:0x3800
	v_add_f32_e32 v187, v68, v187
	v_exp_f32_e32 v70, v70
	v_add_f32_e32 v187, v69, v187
	v_exp_f32_e32 v71, v71
	v_add_f32_e32 v187, v70, v187
	s_waitcnt lgkmcnt(10)
	v_mfma_f32_32x32x16_bf16 v[48:63], v[84:87], v[156:159], v[48:63]
	ds_read_b64_tr_b16 v[156:157], v186 offset:0x3200
	ds_read_b64_tr_b16 v[158:159], v186 offset:0x3a00
	s_nop 0
	v_add_f32_e32 v187, v71, v187
	v_cvt_pk_bf16_f32 v64, v64, v65
	v_cvt_pk_bf16_f32 v65, v66, v67
	v_cvt_pk_bf16_f32 v66, v68, v69
	v_cvt_pk_bf16_f32 v67, v70, v71
	s_nop 0
	s_waitcnt lgkmcnt(10)
	v_mfma_f32_32x32x16_bf16 v[0:15], v[64:67], v[164:167], v[0:15]
	ds_read_b64_tr_b16 v[164:165], v186 offset:0x3400
	ds_read_b64_tr_b16 v[166:167], v186 offset:0x3c00
	v_exp_f32_e32 v72, v72
	v_exp_f32_e32 v73, v73
	v_add_f32_e32 v187, v72, v187
	v_exp_f32_e32 v74, v74
	v_add_f32_e32 v187, v73, v187
	s_waitcnt lgkmcnt(10)
; #define SBAR() __builtin_amdgcn_sched_barrier(0)
; #define SLOAD(i, k0) do { const int sv_ = (k0) * (ldv * 2), sk_ = (k0) * (ldk * 2); sr_[i].vs0 = BLD(rsV, vg0 * 2, sv_); sr_[i].vs1 = BLD(rsV, vg1 * 2, sv_); \
;     _Pragma("unroll") for (int q_ = 0; q_ < KPT; ++q_) sr_[i].ks[q_] = BLD(rsK, kg[q_] * 2, sk_); } while (0)
; #define SWRITE(b, i) do { *(bf16x8*)(V_lds + (b) * SHM_V + vst0) = sr_[i].vs0; *(bf16x8*)(V_lds + (b) * SHM_V + vst1) = sr_[i].vs1; \
;     _Pragma("unroll") for (int q_ = 0; q_ < KPT; ++q_) *(bf16x8*)(K_lds + (b) * SHM_K + kst[q_]) = sr_[i].ks[q_]; } while (0)
;     ...
;       if constexpr (DQK == 64 && ATT_KEARLY) {
;         bf16x8 ka[4], kq[4]; const char* Ks = K_lds + b * SHM_K;
; #pragma unroll
;         for (int d0 = 0; d0 < 4; ++d0) { const int cb = (d0 * 16 + hi * 8) * 2;
;           ka[d0] = *reinterpret_cast<const bf16x8*>(Ks + KSWZ(KP, r32, cb)); kq[d0] = *reinterpret_cast<const bf16x8*>(Ks + KSWZ(KP, 32 + r32, cb)); }
;         SBAR();
;         if constexpr (!(ATT_STAGE_LATE & 1)) { if (j + 1 < nt) { SWRITE(b ^ 1, 0); } if (j + 2 < nt) { SLOAD(0, (j + 2) * KVBLK); } SBAR(); }
;         pA0 = f32x16{}; pA1 = f32x16{};
; #pragma unroll
;         for (int d0 = 0; d0 < 4; ++d0) { pA0 = __builtin_amdgcn_mfma_f32_32x32x16_bf16(ka[d0], qr[d0], pA0, 0, 0, 0); pA1 = __builtin_amdgcn_mfma_f32_32x32x16_bf16(kq[d0], qr[d0], pA1, 0, 0, 0); }
;         SBAR();
;         if constexpr (ATT_STAGE_LATE & 1) { if (j + 1 < nt) { SWRITE(b ^ 1, 0); } if (j + 2 < nt) { SLOAD(0, (j + 2) * KVBLK); } SBAR(); }
;       } else {
;       constexpr bool LATE = (DQK == 128) ? ((ATT_STAGE_LATE & 2) != 0) : ((ATT_STAGE_LATE & 4) != 0);
;       if constexpr (!LATE) { if (j + 1 < nt) { SWRITE(b ^ 1, 0); } if (j + 2 < nt) { SLOAD(0, (j + 2) * KVBLK); } }
;       SBAR(); qkt<DQK>(pA0, pA1, K_lds + b * SHM_K, qr, r32, hi); SBAR();
;       if constexpr (LATE) { if (j + 1 < nt) { SWRITE(b ^ 1, 0); } if (j + 2 < nt) { SLOAD(0, (j + 2) * KVBLK); } SBAR(); }
;       }
;       const int vb = vb0 + b * SHM_V;
;       if constexpr (DQK != 192) {
;         VF f0, f1; v_issue<0>(f0, vb);
;         partialSM<FIXM>(pA0, pA1, m_reg, mnA, alA, C, thrS, kb0 + j * KVBLK, hi);
;         RESC(alA);
;         finishSM<FIXM>(pA0, pA1, alA, l_reg, pa0, pa1, pa2, pa3, kb0 + j * KVBLK, hi); SBAR();
;         pv_pipe(o, vb, f0, f1, pa0, pa1, pa2, pa3);
	v_mfma_f32_32x32x16_bf16 v[16:31], v[64:67], v[176:179], v[16:31]
	ds_read_b64_tr_b16 v[176:177], v186 offset:0x3600
	ds_read_b64_tr_b16 v[178:179], v186 offset:0x3e00
	v_exp_f32_e32 v75, v75
	v_add_f32_e32 v187, v74, v187
	v_exp_f32_e32 v76, v76
	v_add_f32_e32 v187, v75, v187
	v_exp_f32_e32 v77, v77
	s_waitcnt lgkmcnt(10)
	v_mfma_f32_32x32x16_bf16 v[32:47], v[64:67], v[152:155], v[32:47]
	v_add_f32_e32 v187, v76, v187
	v_exp_f32_e32 v78, v78
	v_add_f32_e32 v187, v77, v187
	v_exp_f32_e32 v79, v79
	v_add_f32_e32 v187, v78, v187
	s_waitcnt lgkmcnt(8)
	v_mfma_f32_32x32x16_bf16 v[48:63], v[64:67], v[160:163], v[48:63]
	s_nop 0
	v_add_f32_e32 v187, v79, v187
	v_cvt_pk_bf16_f32 v68, v72, v73
	v_cvt_pk_bf16_f32 v69, v74, v75
	v_cvt_pk_bf16_f32 v70, v76, v77
	v_cvt_pk_bf16_f32 v71, v78, v79
	s_nop 0
	s_waitcnt lgkmcnt(6)
	v_mfma_f32_32x32x16_bf16 v[0:15], v[68:71], v[148:151], v[0:15]
	v_add_f32_e32 v142, v142, v187
	v_add_u32_e32 v188, s6, v135
	s_waitcnt vmcnt(2)
	ds_write_b128 v188, v[120:123]
	v_add_u32_e32 v188, s6, v136
	s_waitcnt vmcnt(1)
	ds_write_b128 v188, v[116:119]
	s_waitcnt lgkmcnt(6)
	v_mfma_f32_32x32x16_bf16 v[16:31], v[68:71], v[156:159], v[16:31]
	v_lshl_add_u32 v188, s3, 13, v139
	s_waitcnt vmcnt(0)
	ds_write_b128 v188, v[124:127]
	s_mov_b32 s38, s30
	s_mov_b32 s39, s31
	s_waitcnt lgkmcnt(5)
	v_mfma_f32_32x32x16_bf16 v[32:47], v[68:71], v[164:167], v[32:47]
	buffer_load_dwordx4 v[120:123], v140, s[28:31], s1 offen
	buffer_load_dwordx4 v[116:119], v141, s[28:31], s1 offen
	buffer_load_dwordx4 v[124:127], v128, s[36:39], s1 offen
	s_add_i32 s0, s0, 1
	s_add_i32 s1, s1, 0xb8000
	s_cmp_eq_u32 s1, 0xb8b8000
	s_waitcnt lgkmcnt(3)
	v_mfma_f32_32x32x16_bf16 v[48:63], v[68:71], v[176:179], v[48:63]
	s_cbranch_scc0 .LBB0_501
	v_add_u32_e32 v128, v143, v147
	v_add_u32_e32 v135, v143, v146
	v_add_u32_e32 v140, v143, v145
	v_add_u32_e32 v141, v143, v144
	s_waitcnt lgkmcnt(0)
	s_barrier
	ds_read_b128 v[64:67], v128 offset:8192
	ds_read_b128 v[68:71], v128 offset:12288
	ds_read_b128 v[146:149], v135 offset:8192
	ds_read_b128 v[150:153], v135 offset:12288
	ds_read_b128 v[154:157], v140 offset:8192
	ds_read_b128 v[158:161], v140 offset:12288
	ds_read_b128 v[162:165], v141 offset:8192
	ds_read_b128 v[172:175], v141 offset:12288
	s_waitcnt lgkmcnt(7)
	v_mfma_f32_32x32x16_bf16 v[80:95], v[64:67], v[112:115], 0
	s_waitcnt lgkmcnt(6)
	v_mfma_f32_32x32x16_bf16 v[64:79], v[68:71], v[112:115], 0
	s_waitcnt lgkmcnt(4)
	v_mfma_f32_32x32x16_bf16 v[64:79], v[150:153], v[108:111], v[64:79]
	v_mfma_f32_32x32x16_bf16 v[80:95], v[146:149], v[108:111], v[80:95]
	s_waitcnt lgkmcnt(2)
	v_mfma_f32_32x32x16_bf16 v[64:79], v[158:161], v[104:107], v[64:79]
	v_mfma_f32_32x32x16_bf16 v[80:95], v[154:157], v[104:107], v[80:95]
	s_waitcnt lgkmcnt(0)
	v_mfma_f32_32x32x16_bf16 v[64:79], v[172:175], v[100:103], v[64:79]
	v_mfma_f32_32x32x16_bf16 v[80:95], v[162:165], v[100:103], v[80:95]
	s_waitcnt vmcnt(2)
	ds_write_b128 v137, v[120:123]
	s_waitcnt vmcnt(1)
	ds_write_b128 v138, v[116:119]
	s_waitcnt vmcnt(0)
	ds_write_b128 v139, v[124:127]
	s_nop 5
	v_exp_f32_e32 v80, v80
	v_exp_f32_e32 v81, v81
	v_exp_f32_e32 v82, v82
	v_exp_f32_e32 v83, v83
	v_exp_f32_e32 v84, v84
	v_exp_f32_e32 v144, v64
	v_add_f32_e32 v64, 0, v80
	v_exp_f32_e32 v85, v85
	v_add_f32_e32 v64, v81, v64
	v_exp_f32_e32 v86, v86
	v_add_f32_e32 v64, v82, v64
	v_exp_f32_e32 v87, v87
	v_add_f32_e32 v64, v83, v64
	v_exp_f32_e32 v88, v88
	v_add_f32_e32 v64, v84, v64
	v_exp_f32_e32 v89, v89
	v_add_f32_e32 v64, v85, v64
	v_exp_f32_e32 v90, v90
	v_add_f32_e32 v64, v86, v64
	v_exp_f32_e32 v91, v91
	v_add_f32_e32 v64, v87, v64
	v_exp_f32_e32 v92, v92
	v_add_f32_e32 v64, v88, v64
	v_exp_f32_e32 v93, v93
	v_add_f32_e32 v64, v89, v64
	v_exp_f32_e32 v94, v94
	v_add_f32_e32 v64, v90, v64
	v_exp_f32_e32 v95, v95
	v_add_f32_e32 v64, v91, v64
	v_add_f32_e32 v64, v92, v64
	v_exp_f32_e32 v145, v65
	v_add_f32_e32 v64, v93, v64
	v_exp_f32_e32 v146, v66
	v_add_f32_e32 v64, v94, v64
	v_exp_f32_e32 v147, v67
	v_add_f32_e32 v64, v95, v64
	v_exp_f32_e32 v148, v68
	v_add_f32_e32 v64, v144, v64
	v_exp_f32_e32 v149, v69
	v_add_f32_e32 v64, v145, v64
	v_exp_f32_e32 v150, v70
	v_add_f32_e32 v64, v146, v64
	v_exp_f32_e32 v151, v71
	v_add_f32_e32 v64, v147, v64
	v_exp_f32_e32 v152, v72
	v_add_f32_e32 v64, v148, v64
	v_exp_f32_e32 v153, v73
	v_add_f32_e32 v64, v149, v64
	v_add_u32_e32 v143, 0x4000, v129
	ds_read_b64_tr_b16 v[116:117], v143 offset:0
	v_exp_f32_e32 v154, v74
	v_add_f32_e32 v64, v150, v64
	ds_read_b64_tr_b16 v[118:119], v143 offset:0x800
	v_exp_f32_e32 v155, v75
	v_add_f32_e32 v64, v151, v64
	ds_read_b64_tr_b16 v[120:121], v143 offset:0x1000
	v_exp_f32_e32 v156, v76
	v_add_f32_e32 v64, v152, v64
	ds_read_b64_tr_b16 v[122:123], v143 offset:0x1800
	v_exp_f32_e32 v157, v77
	v_add_f32_e32 v64, v153, v64
	ds_read_b64_tr_b16 v[124:125], v143 offset:0x2000
	v_exp_f32_e32 v158, v78
	v_add_f32_e32 v64, v154, v64
	ds_read_b64_tr_b16 v[126:127], v143 offset:0x2800
	v_exp_f32_e32 v79, v79
	v_add_f32_e32 v64, v155, v64
	ds_read_b64_tr_b16 v[136:137], v143 offset:0x3000
	v_add_f32_e32 v64, v156, v64
	ds_read_b64_tr_b16 v[138:139], v143 offset:0x3800
	v_add_f32_e32 v64, v157, v64
	v_add_f32_e32 v64, v158, v64
	v_add_f32_e32 v64, v79, v64
	v_add_f32_e32 v142, v142, v64
	v_cvt_pk_bf16_f32 v64, v80, v81
	v_cvt_pk_bf16_f32 v65, v82, v83
	v_cvt_pk_bf16_f32 v66, v84, v85
	v_cvt_pk_bf16_f32 v67, v86, v87
	v_cvt_pk_bf16_f32 v68, v88, v89
	v_cvt_pk_bf16_f32 v69, v90, v91
	v_cvt_pk_bf16_f32 v70, v92, v93
	v_cvt_pk_bf16_f32 v71, v94, v95
	v_cvt_pk_bf16_f32 v72, v144, v145
	v_cvt_pk_bf16_f32 v73, v146, v147
	v_cvt_pk_bf16_f32 v74, v148, v149
	v_cvt_pk_bf16_f32 v75, v150, v151
	v_cvt_pk_bf16_f32 v76, v152, v153
	v_cvt_pk_bf16_f32 v77, v154, v155
	v_cvt_pk_bf16_f32 v78, v156, v157
	v_cvt_pk_bf16_f32 v79, v158, v79
	ds_read_b64_tr_b16 v[80:81], v143 offset:0x200
	ds_read_b64_tr_b16 v[82:83], v143 offset:0xa00
	ds_read_b64_tr_b16 v[84:85], v143 offset:0x1200
	ds_read_b64_tr_b16 v[86:87], v143 offset:0x1a00
	ds_read_b64_tr_b16 v[88:89], v143 offset:0x2200
	ds_read_b64_tr_b16 v[90:91], v143 offset:0x2a00
	ds_read_b64_tr_b16 v[92:93], v143 offset:0x3200
	ds_read_b64_tr_b16 v[94:95], v143 offset:0x3a00
	s_waitcnt lgkmcnt(8)
; #define SBAR() __builtin_amdgcn_sched_barrier(0)
; #define RESC(a) do { if constexpr (!FIXM) if (__any((a) < 1.f)) { if (hi == 0) al_l[r32] = (a); asm volatile("s_waitcnt lgkmcnt(0)" ::: "memory"); \
;     _Pragma("unroll") for (int d = 0; d < 4; ++d) _Pragma("unroll") for (int r = 0; r < 16; ++r) o[d][r] *= al_l[crow(r, hi)]; } } while (0)
; __device__ __forceinline__ void pv_mma(f32x16& od, const VF& f, bf16x8 pa0, bf16x8 pa1, bf16x8 pa2, bf16x8 pa3) {
;     ...
;   od = __builtin_amdgcn_mfma_f32_32x32x16_bf16(pa0, PK(f.l0, f.h0), od, 0, 0, 0);
;   od = __builtin_amdgcn_mfma_f32_32x32x16_bf16(pa1, PK(f.l1, f.h1), od, 0, 0, 0);
;   od = __builtin_amdgcn_mfma_f32_32x32x16_bf16(pa2, PK(f.l2, f.h2), od, 0, 0, 0);
;   od = __builtin_amdgcn_mfma_f32_32x32x16_bf16(pa3, PK(f.l3, f.h3), od, 0, 0, 0);
;     ...
; }
;     ...
;       const int vb = vb0 + b * SHM_V;
;       if constexpr (DQK != 192) {
;         VF f0, f1; v_issue<0>(f0, vb);
;         partialSM<FIXM>(pA0, pA1, m_reg, mnA, alA, C, thrS, kb0 + j * KVBLK, hi);
;         RESC(alA);
;         finishSM<FIXM>(pA0, pA1, alA, l_reg, pa0, pa1, pa2, pa3, kb0 + j * KVBLK, hi); SBAR();
;         pv_pipe(o, vb, f0, f1, pa0, pa1, pa2, pa3);
	s_nop 0
	v_mfma_f32_32x32x16_bf16 v[0:15], v[64:67], v[116:119], v[0:15]
	v_mfma_f32_32x32x16_bf16 v[0:15], v[68:71], v[120:123], v[0:15]
	v_mfma_f32_32x32x16_bf16 v[0:15], v[72:75], v[124:127], v[0:15]
	v_mfma_f32_32x32x16_bf16 v[0:15], v[76:79], v[136:139], v[0:15]
	ds_read_b64_tr_b16 v[116:117], v143 offset:0x400
	ds_read_b64_tr_b16 v[118:119], v143 offset:0xc00
	ds_read_b64_tr_b16 v[120:121], v143 offset:0x1400
	ds_read_b64_tr_b16 v[122:123], v143 offset:0x1c00
	ds_read_b64_tr_b16 v[124:125], v143 offset:0x2400
	ds_read_b64_tr_b16 v[126:127], v143 offset:0x2c00
	ds_read_b64_tr_b16 v[136:137], v143 offset:0x3400
	ds_read_b64_tr_b16 v[138:139], v143 offset:0x3c00
	s_waitcnt lgkmcnt(8)
	v_mfma_f32_32x32x16_bf16 v[16:31], v[64:67], v[80:83], v[16:31]
	v_mfma_f32_32x32x16_bf16 v[16:31], v[68:71], v[84:87], v[16:31]
	v_mfma_f32_32x32x16_bf16 v[16:31], v[72:75], v[88:91], v[16:31]
	v_mfma_f32_32x32x16_bf16 v[16:31], v[76:79], v[92:95], v[16:31]
	ds_read_b64_tr_b16 v[80:81], v143 offset:0x600
	ds_read_b64_tr_b16 v[82:83], v143 offset:0xe00
	ds_read_b64_tr_b16 v[84:85], v143 offset:0x1600
	ds_read_b64_tr_b16 v[86:87], v143 offset:0x1e00
	ds_read_b64_tr_b16 v[88:89], v143 offset:0x2600
	ds_read_b64_tr_b16 v[90:91], v143 offset:0x2e00
	ds_read_b64_tr_b16 v[92:93], v143 offset:0x3600
	ds_read_b64_tr_b16 v[94:95], v143 offset:0x3e00
	s_waitcnt lgkmcnt(8)
	v_mfma_f32_32x32x16_bf16 v[32:47], v[64:67], v[116:119], v[32:47]
	v_mfma_f32_32x32x16_bf16 v[32:47], v[68:71], v[120:123], v[32:47]
	v_mfma_f32_32x32x16_bf16 v[32:47], v[72:75], v[124:127], v[32:47]
	v_mfma_f32_32x32x16_bf16 v[32:47], v[76:79], v[136:139], v[32:47]
	s_waitcnt lgkmcnt(0)
	v_mfma_f32_32x32x16_bf16 v[48:63], v[64:67], v[80:83], v[48:63]
	s_waitcnt lgkmcnt(0)
	s_barrier
; #define SBAR() __builtin_amdgcn_sched_barrier(0)
; __device__ __forceinline__ int crow(int r, int hi) { return (r & 3) + 8 * (r >> 2) + 4 * hi; }
; #define RESC(a) do { if constexpr (!FIXM) if (__any((a) < 1.f)) { if (hi == 0) al_l[r32] = (a); asm volatile("s_waitcnt lgkmcnt(0)" ::: "memory"); \
;     _Pragma("unroll") for (int d = 0; d < 4; ++d) _Pragma("unroll") for (int r = 0; r < 16; ++r) o[d][r] *= al_l[crow(r, hi)]; } } while (0)
;     ...
;       const int vb = vb0 + b * SHM_V;
;       if constexpr (DQK != 192) {
;         VF f0, f1; v_issue<0>(f0, vb);
;         partialSM<FIXM>(pA0, pA1, m_reg, mnA, alA, C, thrS, kb0 + j * KVBLK, hi);
;         RESC(alA);
;         finishSM<FIXM>(pA0, pA1, alA, l_reg, pa0, pa1, pa2, pa3, kb0 + j * KVBLK, hi); SBAR();
;         pv_pipe(o, vb, f0, f1, pa0, pa1, pa2, pa3);
;     ...
;   { auto rr = __builtin_amdgcn_permlane32_swap(__float_as_uint(l_reg), __float_as_uint(l_reg), false, false);
;     l_reg = __uint_as_float(rr[0]) + __uint_as_float(rr[1]); }
;   if constexpr (SPLIT) if (part != nullptr) {
;     if (wid == 0) {
; #pragma unroll
;       for (int r = 0; r < 16; ++r) { const int orow = crow(r, hi);
;         if (orow < 16) {
; #pragma unroll
;           for (int d0 = 0; d0 < 4; ++d0) part[orow * 132 + d0 * 32 + r32] = o[d0][r]; } }
;       if (hi == 0 && r32 < 16) { part[r32 * 132 + 128] = m_reg; part[r32 * 132 + 129] = l_reg; }
;     }
;     __syncthreads();
;     return;
;   }
;   if (hi == 0) li_l[r32] = l_reg; asm volatile("s_waitcnt lgkmcnt(0)" ::: "memory");
; #pragma unroll
;   for (int r = 0; r < 16; ++r) { const int orow = wid * QBLK + crow(r, hi); const float rli = __builtin_amdgcn_rcpf(li_l[crow(r, hi)]);
;     if (orow < nvalid) {
;       if constexpr (MODE == 0) {
; #pragma unroll
;         for (int d0 = 0; d0 < 4; ++d0) Of[(long)orow * ldo + d0 * 32 + r32] = o[d0][r] * rli;
	v_and_b32_e32 v120, 0x3fffffc0, v134
	v_mfma_f32_32x32x16_bf16 v[48:63], v[68:71], v[84:87], v[48:63]
	v_mfma_f32_32x32x16_bf16 v[48:63], v[72:75], v[88:91], v[48:63]
	ds_read_b128 v[64:67], v128
	ds_read_b128 v[80:83], v135
	ds_read_b128 v[84:87], v140
	ds_read_b128 v[88:91], v141
	v_mfma_f32_32x32x16_bf16 v[48:63], v[76:79], v[92:95], v[48:63]
	s_waitcnt lgkmcnt(3)
	v_mfma_f32_32x32x16_bf16 v[64:79], v[64:67], v[112:115], 0
	s_waitcnt lgkmcnt(2)
	v_mfma_f32_32x32x16_bf16 v[64:79], v[80:83], v[108:111], v[64:79]
	s_waitcnt lgkmcnt(1)
	v_mfma_f32_32x32x16_bf16 v[64:79], v[84:87], v[104:107], v[64:79]
	s_waitcnt lgkmcnt(0)
	v_mfma_f32_32x32x16_bf16 v[64:79], v[88:91], v[100:103], v[64:79]
	s_nop 11
	v_exp_f32_e32 v88, v64
	v_exp_f32_e32 v65, v65
	v_exp_f32_e32 v89, v66
	v_exp_f32_e32 v67, v67
	ds_read_b64_tr_b16 v[72:73], v129 offset:0
	v_exp_f32_e32 v68, v68
	v_add_f32_e32 v64, 0, v88
	ds_read_b64_tr_b16 v[74:75], v129 offset:0x800
	v_exp_f32_e32 v69, v69
	v_add_f32_e32 v64, v65, v64
	ds_read_b64_tr_b16 v[76:77], v129 offset:0x1000
	v_exp_f32_e32 v70, v70
	v_add_f32_e32 v64, v89, v64
	ds_read_b64_tr_b16 v[78:79], v129 offset:0x1800
	v_exp_f32_e32 v71, v71
	v_add_f32_e32 v64, v67, v64
	ds_read_b64_tr_b16 v[80:81], v129 offset:0x2000
	v_add_f32_e32 v64, v68, v64
	ds_read_b64_tr_b16 v[82:83], v129 offset:0x2800
	v_add_f32_e32 v64, v69, v64
	ds_read_b64_tr_b16 v[84:85], v129 offset:0x3000
	v_add_f32_e32 v64, v70, v64
	ds_read_b64_tr_b16 v[86:87], v129 offset:0x3800
	v_add_f32_e32 v64, v71, v64
	v_add_f32_e32 v64, 0, v64
	v_add_f32_e32 v64, v142, v64
	v_cvt_pk_bf16_f32 v66, v88, v65
	v_cvt_pk_bf16_f32 v67, v89, v67
	v_cvt_pk_bf16_f32 v68, v68, v69
	v_cvt_pk_bf16_f32 v69, v70, v71
	v_cvt_pk_bf16_f32 v88, v169, v169
	v_cvt_pk_bf16_f32 v89, v169, v169
	v_cvt_pk_bf16_f32 v90, v169, v169
	v_cvt_pk_bf16_f32 v91, v169, v169
	v_cvt_pk_bf16_f32 v92, v169, v169
	v_cvt_pk_bf16_f32 v93, v169, v169
	v_cvt_pk_bf16_f32 v94, v169, v169
	v_cvt_pk_bf16_f32 v95, v169, v169
	v_cvt_pk_bf16_f32 v100, v169, v169
	v_cvt_pk_bf16_f32 v101, v169, v169
	v_cvt_pk_bf16_f32 v102, v169, v169
	v_cvt_pk_bf16_f32 v103, v169, v169
	ds_read_b64_tr_b16 v[104:105], v129 offset:0x200
	ds_read_b64_tr_b16 v[106:107], v129 offset:0xa00
	ds_read_b64_tr_b16 v[108:109], v129 offset:0x1200
	ds_read_b64_tr_b16 v[110:111], v129 offset:0x1a00
	ds_read_b64_tr_b16 v[112:113], v129 offset:0x2200
	ds_read_b64_tr_b16 v[114:115], v129 offset:0x2a00
	ds_read_b64_tr_b16 v[116:117], v129 offset:0x3200
	ds_read_b64_tr_b16 v[118:119], v129 offset:0x3a00
	s_waitcnt lgkmcnt(8)
	s_nop 0
	v_mfma_f32_32x32x16_bf16 v[0:15], v[66:69], v[72:75], v[0:15]
	v_mfma_f32_32x32x16_bf16 v[0:15], v[88:91], v[76:79], v[0:15]
	v_mfma_f32_32x32x16_bf16 v[0:15], v[92:95], v[80:83], v[0:15]
	v_mfma_f32_32x32x16_bf16 v[0:15], v[100:103], v[84:87], v[0:15]
	ds_read_b64_tr_b16 v[70:71], v129 offset:0x400
	ds_read_b64_tr_b16 v[72:73], v129 offset:0xc00
	ds_read_b64_tr_b16 v[74:75], v129 offset:0x1400
	ds_read_b64_tr_b16 v[76:77], v129 offset:0x1c00
	ds_read_b64_tr_b16 v[78:79], v129 offset:0x2400
	ds_read_b64_tr_b16 v[80:81], v129 offset:0x2c00
	ds_read_b64_tr_b16 v[82:83], v129 offset:0x3400
	ds_read_b64_tr_b16 v[84:85], v129 offset:0x3c00
	s_waitcnt lgkmcnt(8)
	v_mfma_f32_32x32x16_bf16 v[16:31], v[66:69], v[104:107], v[16:31]
	v_mfma_f32_32x32x16_bf16 v[16:31], v[88:91], v[108:111], v[16:31]
	v_mfma_f32_32x32x16_bf16 v[16:31], v[92:95], v[112:115], v[16:31]
	v_mfma_f32_32x32x16_bf16 v[16:31], v[100:103], v[116:119], v[16:31]
	ds_read_b64_tr_b16 v[104:105], v129 offset:0x600
	ds_read_b64_tr_b16 v[106:107], v129 offset:0xe00
	ds_read_b64_tr_b16 v[108:109], v129 offset:0x1600
	ds_read_b64_tr_b16 v[110:111], v129 offset:0x1e00
	ds_read_b64_tr_b16 v[112:113], v129 offset:0x2600
	ds_read_b64_tr_b16 v[114:115], v129 offset:0x2e00
	ds_read_b64_tr_b16 v[116:117], v129 offset:0x3600
	ds_read_b64_tr_b16 v[118:119], v129 offset:0x3e00
	s_waitcnt lgkmcnt(8)
	v_mfma_f32_32x32x16_bf16 v[32:47], v[66:69], v[70:73], v[32:47]
	v_mfma_f32_32x32x16_bf16 v[32:47], v[88:91], v[74:77], v[32:47]
	v_mfma_f32_32x32x16_bf16 v[32:47], v[92:95], v[78:81], v[32:47]
	v_mfma_f32_32x32x16_bf16 v[32:47], v[100:103], v[82:85], v[32:47]
	s_waitcnt lgkmcnt(0)
	v_mfma_f32_32x32x16_bf16 v[48:63], v[66:69], v[104:107], v[48:63]
	s_add_i32 s0, 0, 0x20000
	v_mov_b32_e32 v65, v64
	v_lshl_add_u32 v67, v120, 2, s0
	s_nop 0
	v_permlane32_swap_b32_e32 v64, v65
	v_cmp_gt_u32_e32 vcc, 32, v133
	v_mfma_f32_32x32x16_bf16 v[48:63], v[88:91], v[108:111], v[48:63]
	v_mfma_f32_32x32x16_bf16 v[48:63], v[92:95], v[112:115], v[48:63]
	v_mfma_f32_32x32x16_bf16 v[48:63], v[100:103], v[116:119], v[48:63]
	s_and_saveexec_b64 s[0:1], vcc
	v_lshl_add_u32 v66, v131, 2, v67
	v_add_f32_e32 v64, v64, v65
	ds_write_b32 v66, v64
	s_or_b64 exec, exec, s[0:1]
	s_lshl_b32 s0, s97, 7
	s_lshl_b64 s[2:3], s[4:5], 12
	s_ashr_i32 s1, s0, 31
	v_readlane_b32 s6, v252, 47
	s_add_u32 s2, s6, s2
	v_readlane_b32 s6, v252, 48
	s_addc_u32 s3, s6, s3
	s_lshl_b64 s[0:1], s[0:1], 2
	s_add_u32 s0, s2, s0
	s_waitcnt lgkmcnt(0)
	v_lshlrev_b32_e32 v69, 2, v132
	s_addc_u32 s1, s3, s1
	v_lshlrev_b32_e32 v64, 2, v131
	v_mov_b32_e32 v65, v169
	v_or_b32_e32 v66, v69, v130
	v_lshl_add_u64 v[64:65], s[0:1], 0, v[64:65]
	v_cmp_gt_i32_e32 vcc, s96, v66
	v_lshl_add_u32 v68, v69, 2, v67
	s_and_saveexec_b64 s[0:1], vcc
	s_cbranch_execz .LBB0_506
	ds_read_b32 v67, v68
	s_waitcnt lgkmcnt(0)
	v_rcp_f32_e32 v70, v67
	v_ashrrev_i32_e32 v67, 31, v66
	v_lshlrev_b64 v[66:67], 12, v[66:67]
	v_lshl_add_u64 v[66:67], v[64:65], 0, v[66:67]
	v_mul_f32_e32 v0, v0, v70
	v_mul_f32_e32 v16, v16, v70
	v_mul_f32_e32 v32, v32, v70
	global_store_dword v[66:67], v0, off
	global_store_dword v[66:67], v16, off offset:128
	global_store_dword v[66:67], v32, off offset:256
	v_mul_f32_e32 v0, v48, v70
	global_store_dword v[66:67], v0, off offset:384

; #define SBAR() __builtin_amdgcn_sched_barrier(0)
; template <int D0> __device__ __forceinline__ void pv_one(f32x16& od, int vb, bf16x8 pa0, bf16x8 pa1, bf16x8 pa2, bf16x8 pa3) {
;   const s16x4 l0 = tr_read<v_rd_off(D0, 0, 0)>(vb), h0 = tr_read<v_rd_off(D0, 0, 1)>(vb), l1 = tr_read<v_rd_off(D0, 1, 0)>(vb), h1 = tr_read<v_rd_off(D0, 1, 1)>(vb);
;   const s16x4 l2 = tr_read<v_rd_off(D0, 2, 0)>(vb), h2 = tr_read<v_rd_off(D0, 2, 1)>(vb), l3 = tr_read<v_rd_off(D0, 3, 0)>(vb), h3 = tr_read<v_rd_off(D0, 3, 1)>(vb);
;   asm volatile("s_waitcnt lgkmcnt(0)" ::: "memory"); SBAR();
;     ...
;   od = __builtin_amdgcn_mfma_f32_32x32x16_bf16(pa0, PK(l0, h0), od, 0, 0, 0);
;   od = __builtin_amdgcn_mfma_f32_32x32x16_bf16(pa1, PK(l1, h1), od, 0, 0, 0);
;   od = __builtin_amdgcn_mfma_f32_32x32x16_bf16(pa2, PK(l2, h2), od, 0, 0, 0);
;   od = __builtin_amdgcn_mfma_f32_32x32x16_bf16(pa3, PK(l3, h3), od, 0, 0, 0);
;     ...
; }
; __device__ __forceinline__ void pv_d0(f32x16* o, int vb, bf16x8 pa0, bf16x8 pa1, bf16x8 pa2, bf16x8 pa3) {
;   pv_one<0>(o[0], vb, pa0, pa1, pa2, pa3); pv_one<1>(o[1], vb, pa0, pa1, pa2, pa3); pv_one<2>(o[2], vb, pa0, pa1, pa2, pa3); pv_one<3>(o[3], vb, pa0, pa1, pa2, pa3);
;     ...
;       constexpr bool LATE = (DQK == 128) ? ((ATT_STAGE_LATE & 2) != 0) : ((ATT_STAGE_LATE & 4) != 0);
;       if constexpr (!LATE) { if (j + 1 < nt) { SWRITE(b ^ 1, 0); } if (j + 2 < nt) { SLOAD(0, (j + 2) * KVBLK); } }
;       SBAR(); qkt<DQK>(pA0, pA1, K_lds + b * SHM_K, qr, r32, hi); SBAR();
;       if constexpr (LATE) { if (j + 1 < nt) { SWRITE(b ^ 1, 0); } if (j + 2 < nt) { SLOAD(0, (j + 2) * KVBLK); } SBAR(); }
;       }
;       const int vb = vb0 + b * SHM_V;
;       if constexpr (DQK != 192) {
;         VF f0, f1; v_issue<0>(f0, vb);
;         partialSM<FIXM>(pA0, pA1, m_reg, mnA, alA, C, thrS, kb0 + j * KVBLK, hi);
;         RESC(alA);
;         finishSM<FIXM>(pA0, pA1, alA, l_reg, pa0, pa1, pa2, pa3, kb0 + j * KVBLK, hi); SBAR();
;         pv_pipe(o, vb, f0, f1, pa0, pa1, pa2, pa3);
;       } else {
;         partialSM<FIXM>(pA0, pA1, m_reg, mnA, alA, C, thrS, kb0 + j * KVBLK, hi);
;         RESC(alA);
;         finishSM<FIXM>(pA0, pA1, alA, l_reg, pa0, pa1, pa2, pa3, kb0 + j * KVBLK, hi); SBAR();
;         pv_d0(o, vb, pa0, pa1, pa2, pa3);
.LBB0_578:
	s_and_b32 s6, s1, 1
	s_waitcnt lgkmcnt(0)
	s_barrier
	s_mul_i32 s7, s6, 0x6000
	s_add_i32 s7, s0, s7
	v_add3_u32 v218, s7, v224, v189
	v_add3_u32 v219, s7, v223, v189
	v_add3_u32 v220, s7, v222, v189
	v_add3_u32 v242, s7, v221, v189
	ds_read_b128 v[172:175], v218
	ds_read_b128 v[176:179], v218 offset:12288
	ds_read_b128 v[238:241], v219
	ds_read_b128 v[214:217], v219 offset:12288
	s_waitcnt lgkmcnt(3)
	v_mfma_f32_32x32x16_bf16 v[80:95], v[172:175], v[144:147], 0
	ds_read_b128 v[172:175], v220
	s_waitcnt lgkmcnt(3)
	v_mfma_f32_32x32x16_bf16 v[64:79], v[176:179], v[144:147], 0
	ds_read_b128 v[176:179], v220 offset:12288
	s_waitcnt lgkmcnt(3)
	v_mfma_f32_32x32x16_bf16 v[80:95], v[238:241], v[140:143], v[80:95]
	ds_read_b128 v[238:241], v242
	s_waitcnt lgkmcnt(3)
	v_mfma_f32_32x32x16_bf16 v[64:79], v[214:217], v[140:143], v[64:79]
	ds_read_b128 v[214:217], v242 offset:12288
	s_waitcnt lgkmcnt(3)
	v_mfma_f32_32x32x16_bf16 v[80:95], v[172:175], v[136:139], v[80:95]
	ds_read_b128 v[172:175], v218 offset:128
	s_waitcnt lgkmcnt(3)
	v_mfma_f32_32x32x16_bf16 v[64:79], v[176:179], v[136:139], v[64:79]
	ds_read_b128 v[176:179], v218 offset:12416
	s_waitcnt lgkmcnt(3)
	v_mfma_f32_32x32x16_bf16 v[80:95], v[238:241], v[132:135], v[80:95]
	ds_read_b128 v[238:241], v219 offset:128
	s_waitcnt lgkmcnt(3)
	v_mfma_f32_32x32x16_bf16 v[64:79], v[214:217], v[132:135], v[64:79]
	ds_read_b128 v[214:217], v219 offset:12416
	s_waitcnt lgkmcnt(3)
	v_mfma_f32_32x32x16_bf16 v[80:95], v[172:175], v[128:131], v[80:95]
	ds_read_b128 v[172:175], v220 offset:128
	s_waitcnt lgkmcnt(3)
	v_mfma_f32_32x32x16_bf16 v[64:79], v[176:179], v[128:131], v[64:79]
	ds_read_b128 v[176:179], v220 offset:12416
	s_waitcnt lgkmcnt(3)
	v_mfma_f32_32x32x16_bf16 v[80:95], v[238:241], v[124:127], v[80:95]
	ds_read_b128 v[238:241], v242 offset:128
	s_waitcnt lgkmcnt(3)
	v_mfma_f32_32x32x16_bf16 v[64:79], v[214:217], v[124:127], v[64:79]
	ds_read_b128 v[214:217], v242 offset:12416
	s_waitcnt lgkmcnt(3)
	v_mfma_f32_32x32x16_bf16 v[80:95], v[172:175], v[120:123], v[80:95]
	ds_read_b128 v[172:175], v218 offset:256
	s_waitcnt lgkmcnt(3)
	v_mfma_f32_32x32x16_bf16 v[64:79], v[176:179], v[120:123], v[64:79]
	ds_read_b128 v[176:179], v218 offset:12544
	s_waitcnt lgkmcnt(3)
	v_mfma_f32_32x32x16_bf16 v[80:95], v[238:241], v[116:119], v[80:95]
	ds_read_b128 v[238:241], v219 offset:256
	s_waitcnt lgkmcnt(3)
	v_mfma_f32_32x32x16_bf16 v[64:79], v[214:217], v[116:119], v[64:79]
	ds_read_b128 v[214:217], v219 offset:12544
	s_waitcnt lgkmcnt(3)
	v_mfma_f32_32x32x16_bf16 v[80:95], v[172:175], v[112:115], v[80:95]
	ds_read_b128 v[172:175], v220 offset:256
	s_waitcnt lgkmcnt(3)
	v_mfma_f32_32x32x16_bf16 v[64:79], v[176:179], v[112:115], v[64:79]
	ds_read_b128 v[176:179], v220 offset:12544
	s_waitcnt lgkmcnt(3)
	v_mfma_f32_32x32x16_bf16 v[80:95], v[238:241], v[108:111], v[80:95]
	ds_read_b128 v[238:241], v242 offset:256
	s_waitcnt lgkmcnt(3)
	v_mfma_f32_32x32x16_bf16 v[64:79], v[214:217], v[108:111], v[64:79]
	ds_read_b128 v[214:217], v242 offset:12544
	v_lshl_add_u32 v218, s6, 14, v187
	s_waitcnt lgkmcnt(3)
	v_mfma_f32_32x32x16_bf16 v[80:95], v[172:175], v[104:107], v[80:95]
	ds_read_b64_tr_b16 v[172:173], v218 offset:0x0
	ds_read_b64_tr_b16 v[174:175], v218 offset:0x800
	s_waitcnt lgkmcnt(4)
	v_mfma_f32_32x32x16_bf16 v[64:79], v[176:179], v[104:107], v[64:79]
	ds_read_b64_tr_b16 v[176:177], v218 offset:0x200
	ds_read_b64_tr_b16 v[178:179], v218 offset:0xa00
	s_waitcnt lgkmcnt(5)
	v_mfma_f32_32x32x16_bf16 v[80:95], v[238:241], v[100:103], v[80:95]
	ds_read_b64_tr_b16 v[238:239], v218 offset:0x400
	ds_read_b64_tr_b16 v[240:241], v218 offset:0xc00
	s_waitcnt lgkmcnt(6)
	v_mfma_f32_32x32x16_bf16 v[64:79], v[214:217], v[100:103], v[64:79]
	ds_read_b64_tr_b16 v[214:215], v218 offset:0x600
	ds_read_b64_tr_b16 v[216:217], v218 offset:0xe00
	s_nop 7
	s_nop 3
	v_exp_f32_e32 v80, v80
	v_exp_f32_e32 v81, v81
	v_add_f32_e32 v191, 0, v80
	v_exp_f32_e32 v82, v82
	v_add_f32_e32 v191, v81, v191
	v_exp_f32_e32 v83, v83
	v_add_f32_e32 v191, v82, v191
	v_exp_f32_e32 v84, v84
	v_add_f32_e32 v191, v83, v191
	v_exp_f32_e32 v85, v85
	v_add_f32_e32 v191, v84, v191
	v_exp_f32_e32 v86, v86
	v_add_f32_e32 v191, v85, v191
	v_exp_f32_e32 v87, v87
	v_add_f32_e32 v191, v86, v191
	s_nop 0
	v_add_f32_e32 v191, v87, v191
	v_cvt_pk_bf16_f32 v80, v80, v81
	v_cvt_pk_bf16_f32 v81, v82, v83
	v_cvt_pk_bf16_f32 v82, v84, v85
	v_cvt_pk_bf16_f32 v83, v86, v87
	s_nop 1
	s_waitcnt lgkmcnt(6)
	v_mfma_f32_32x32x16_bf16 v[48:63], v[80:83], v[172:175], v[48:63]
	ds_read_b64_tr_b16 v[172:173], v218 offset:0x1000
	ds_read_b64_tr_b16 v[174:175], v218 offset:0x1800
	v_exp_f32_e32 v88, v88
	v_exp_f32_e32 v89, v89
	v_add_f32_e32 v191, v88, v191
	v_exp_f32_e32 v90, v90
	v_add_f32_e32 v191, v89, v191
	s_waitcnt lgkmcnt(6)
	v_mfma_f32_32x32x16_bf16 v[32:47], v[80:83], v[176:179], v[32:47]
	ds_read_b64_tr_b16 v[176:177], v218 offset:0x1200
	ds_read_b64_tr_b16 v[178:179], v218 offset:0x1a00
	v_exp_f32_e32 v91, v91
	v_add_f32_e32 v191, v90, v191
	v_exp_f32_e32 v92, v92
	v_add_f32_e32 v191, v91, v191
	v_exp_f32_e32 v93, v93
	s_waitcnt lgkmcnt(6)
	v_mfma_f32_32x32x16_bf16 v[16:31], v[80:83], v[238:241], v[16:31]
	ds_read_b64_tr_b16 v[238:239], v218 offset:0x1400
	ds_read_b64_tr_b16 v[240:241], v218 offset:0x1c00
	v_add_f32_e32 v191, v92, v191
	v_exp_f32_e32 v94, v94
	v_add_f32_e32 v191, v93, v191
	v_exp_f32_e32 v95, v95
	v_add_f32_e32 v191, v94, v191
	s_waitcnt lgkmcnt(6)
	v_mfma_f32_32x32x16_bf16 v[0:15], v[80:83], v[214:217], v[0:15]
	ds_read_b64_tr_b16 v[214:215], v218 offset:0x1600
	ds_read_b64_tr_b16 v[216:217], v218 offset:0x1e00
	s_nop 0
	v_add_f32_e32 v191, v95, v191
	v_cvt_pk_bf16_f32 v84, v88, v89
	v_cvt_pk_bf16_f32 v85, v90, v91
	v_cvt_pk_bf16_f32 v86, v92, v93
	v_cvt_pk_bf16_f32 v87, v94, v95
	s_nop 0
	s_waitcnt lgkmcnt(6)
; #define SBAR() __builtin_amdgcn_sched_barrier(0)
; #define RESC(a) do { if constexpr (!FIXM) if (__any((a) < 1.f)) { if (hi == 0) al_l[r32] = (a); asm volatile("s_waitcnt lgkmcnt(0)" ::: "memory"); \
;     _Pragma("unroll") for (int d = 0; d < 4; ++d) _Pragma("unroll") for (int r = 0; r < 16; ++r) o[d][r] *= al_l[crow(r, hi)]; } } while (0)
; template <int D0> __device__ __forceinline__ void pv_one(f32x16& od, int vb, bf16x8 pa0, bf16x8 pa1, bf16x8 pa2, bf16x8 pa3) {
;   const s16x4 l0 = tr_read<v_rd_off(D0, 0, 0)>(vb), h0 = tr_read<v_rd_off(D0, 0, 1)>(vb), l1 = tr_read<v_rd_off(D0, 1, 0)>(vb), h1 = tr_read<v_rd_off(D0, 1, 1)>(vb);
;   const s16x4 l2 = tr_read<v_rd_off(D0, 2, 0)>(vb), h2 = tr_read<v_rd_off(D0, 2, 1)>(vb), l3 = tr_read<v_rd_off(D0, 3, 0)>(vb), h3 = tr_read<v_rd_off(D0, 3, 1)>(vb);
;   asm volatile("s_waitcnt lgkmcnt(0)" ::: "memory"); SBAR();
;     ...
;   od = __builtin_amdgcn_mfma_f32_32x32x16_bf16(pa0, PK(l0, h0), od, 0, 0, 0);
;   od = __builtin_amdgcn_mfma_f32_32x32x16_bf16(pa1, PK(l1, h1), od, 0, 0, 0);
;   od = __builtin_amdgcn_mfma_f32_32x32x16_bf16(pa2, PK(l2, h2), od, 0, 0, 0);
;   od = __builtin_amdgcn_mfma_f32_32x32x16_bf16(pa3, PK(l3, h3), od, 0, 0, 0);
;     ...
; }
; __device__ __forceinline__ void pv_d0(f32x16* o, int vb, bf16x8 pa0, bf16x8 pa1, bf16x8 pa2, bf16x8 pa3) {
;   pv_one<0>(o[0], vb, pa0, pa1, pa2, pa3); pv_one<1>(o[1], vb, pa0, pa1, pa2, pa3); pv_one<2>(o[2], vb, pa0, pa1, pa2, pa3); pv_one<3>(o[3], vb, pa0, pa1, pa2, pa3);
;     ...
;       } else {
;         partialSM<FIXM>(pA0, pA1, m_reg, mnA, alA, C, thrS, kb0 + j * KVBLK, hi);
;         RESC(alA);
;         finishSM<FIXM>(pA0, pA1, alA, l_reg, pa0, pa1, pa2, pa3, kb0 + j * KVBLK, hi); SBAR();
;         pv_d0(o, vb, pa0, pa1, pa2, pa3);
	v_mfma_f32_32x32x16_bf16 v[48:63], v[84:87], v[172:175], v[48:63]
	ds_read_b64_tr_b16 v[172:173], v218 offset:0x2000
	ds_read_b64_tr_b16 v[174:175], v218 offset:0x2800
	v_exp_f32_e32 v64, v64
	v_exp_f32_e32 v65, v65
	v_add_f32_e32 v191, v64, v191
	v_exp_f32_e32 v66, v66
	v_add_f32_e32 v191, v65, v191
	s_waitcnt lgkmcnt(6)
	v_mfma_f32_32x32x16_bf16 v[32:47], v[84:87], v[176:179], v[32:47]
	ds_read_b64_tr_b16 v[176:177], v218 offset:0x2200
	ds_read_b64_tr_b16 v[178:179], v218 offset:0x2a00
	v_exp_f32_e32 v67, v67
	v_add_f32_e32 v191, v66, v191
	v_exp_f32_e32 v68, v68
	v_add_f32_e32 v191, v67, v191
	v_exp_f32_e32 v69, v69
	s_waitcnt lgkmcnt(6)
	v_mfma_f32_32x32x16_bf16 v[16:31], v[84:87], v[238:241], v[16:31]
	ds_read_b64_tr_b16 v[238:239], v218 offset:0x2400
	ds_read_b64_tr_b16 v[240:241], v218 offset:0x2c00
	v_add_f32_e32 v191, v68, v191
	v_exp_f32_e32 v70, v70
	v_add_f32_e32 v191, v69, v191
	v_exp_f32_e32 v71, v71
	v_add_f32_e32 v191, v70, v191
	s_waitcnt lgkmcnt(6)
	v_mfma_f32_32x32x16_bf16 v[0:15], v[84:87], v[214:217], v[0:15]
	ds_read_b64_tr_b16 v[214:215], v218 offset:0x2600
	ds_read_b64_tr_b16 v[216:217], v218 offset:0x2e00
	s_nop 0
	v_add_f32_e32 v191, v71, v191
	v_cvt_pk_bf16_f32 v64, v64, v65
	v_cvt_pk_bf16_f32 v65, v66, v67
	v_cvt_pk_bf16_f32 v66, v68, v69
	v_cvt_pk_bf16_f32 v67, v70, v71
	s_nop 0
	s_waitcnt lgkmcnt(6)
	v_mfma_f32_32x32x16_bf16 v[48:63], v[64:67], v[172:175], v[48:63]
	ds_read_b64_tr_b16 v[172:173], v218 offset:0x3000
	ds_read_b64_tr_b16 v[174:175], v218 offset:0x3800
	v_exp_f32_e32 v72, v72
	v_exp_f32_e32 v73, v73
	v_add_f32_e32 v191, v72, v191
	v_exp_f32_e32 v74, v74
	v_add_f32_e32 v191, v73, v191
	s_waitcnt lgkmcnt(6)
	v_mfma_f32_32x32x16_bf16 v[32:47], v[64:67], v[176:179], v[32:47]
	ds_read_b64_tr_b16 v[176:177], v218 offset:0x3200
	ds_read_b64_tr_b16 v[178:179], v218 offset:0x3a00
	v_exp_f32_e32 v75, v75
	v_add_f32_e32 v191, v74, v191
	v_exp_f32_e32 v76, v76
	v_add_f32_e32 v191, v75, v191
	v_exp_f32_e32 v77, v77
	s_waitcnt lgkmcnt(6)
	v_mfma_f32_32x32x16_bf16 v[16:31], v[64:67], v[238:241], v[16:31]
	ds_read_b64_tr_b16 v[238:239], v218 offset:0x3400
	ds_read_b64_tr_b16 v[240:241], v218 offset:0x3c00
	v_add_f32_e32 v191, v76, v191
	v_exp_f32_e32 v78, v78
	v_add_f32_e32 v191, v77, v191
	v_exp_f32_e32 v79, v79
	v_add_f32_e32 v191, v78, v191
	s_waitcnt lgkmcnt(6)
	v_mfma_f32_32x32x16_bf16 v[0:15], v[64:67], v[214:217], v[0:15]
	ds_read_b64_tr_b16 v[214:215], v218 offset:0x3600
	ds_read_b64_tr_b16 v[216:217], v218 offset:0x3e00
	s_nop 0
	v_add_f32_e32 v191, v79, v191
	v_cvt_pk_bf16_f32 v68, v72, v73
	v_cvt_pk_bf16_f32 v69, v74, v75
	v_cvt_pk_bf16_f32 v70, v76, v77
	v_cvt_pk_bf16_f32 v71, v78, v79
	s_nop 0
	s_waitcnt lgkmcnt(6)
	v_mfma_f32_32x32x16_bf16 v[48:63], v[68:71], v[172:175], v[48:63]
	v_add_f32_e32 v230, v230, v191
	s_xor_b32 s7, s6, 1
	s_lshl_b32 s12, s7, 14
	s_mulk_i32 s7, 0x6000
	s_add_i32 s7, s0, s7
	v_add_u32_e32 v219, s12, v236
	s_waitcnt vmcnt(4)
	ds_write_b128 v219, v[152:155]
	v_add_u32_e32 v219, s12, v237
	s_waitcnt vmcnt(3)
	ds_write_b128 v219, v[148:151]
	s_waitcnt lgkmcnt(6)
	v_mfma_f32_32x32x16_bf16 v[32:47], v[68:71], v[176:179], v[32:47]
	v_add_u32_e32 v219, s7, v225
	s_waitcnt vmcnt(2)
	ds_write_b128 v219, v[164:167]
	v_add_u32_e32 v219, s7, v226
	s_waitcnt vmcnt(1)
	ds_write_b128 v219, v[160:163]
	s_waitcnt lgkmcnt(6)
	v_mfma_f32_32x32x16_bf16 v[16:31], v[68:71], v[238:241], v[16:31]
	v_add_u32_e32 v219, s7, v227
	s_waitcnt vmcnt(0)
	ds_write_b128 v219, v[156:159]
	s_mov_b32 s38, s30
	s_mov_b32 s39, s31
	buffer_load_dwordx4 v[152:155], v228, s[28:31], s3 offen
	buffer_load_dwordx4 v[148:151], v229, s[28:31], s3 offen
	buffer_load_dwordx4 v[164:167], v186, s[36:39], s2 offen
	buffer_load_dwordx4 v[160:163], v188, s[36:39], s2 offen
	buffer_load_dwordx4 v[156:159], v190, s[36:39], s2 offen
	s_add_i32 s1, s1, 1
	s_add_i32 s2, s2, 0x18000
	s_add_i32 s3, s3, 0x20000
	s_cmp_eq_u32 s2, 0x1818000
	s_waitcnt lgkmcnt(5)
	v_mfma_f32_32x32x16_bf16 v[0:15], v[68:71], v[214:217], v[0:15]
	s_cbranch_scc0 .LBB0_578
	v_add_u32_e32 v220, 0x80, v224
	v_add_u32_e32 v219, 0x80, v223
	v_add_u32_e32 v218, 0x80, v222
	v_add_u32_e32 v217, 0x80, v221
	v_add_u32_e32 v216, 0x100, v224
	v_add_u32_e32 v215, 0x100, v223
	v_add_u32_e32 v214, 0x100, v222
	v_add_u32_e32 v191, 0x100, v221
	s_waitcnt lgkmcnt(0)
	s_barrier
; #define SBAR() __builtin_amdgcn_sched_barrier(0)
; #define SLOAD(i, k0) do { const int sv_ = (k0) * (ldv * 2), sk_ = (k0) * (ldk * 2); sr_[i].vs0 = BLD(rsV, vg0 * 2, sv_); sr_[i].vs1 = BLD(rsV, vg1 * 2, sv_); \
;     _Pragma("unroll") for (int q_ = 0; q_ < KPT; ++q_) sr_[i].ks[q_] = BLD(rsK, kg[q_] * 2, sk_); } while (0)
; #define SWRITE(b, i) do { *(bf16x8*)(V_lds + (b) * SHM_V + vst0) = sr_[i].vs0; *(bf16x8*)(V_lds + (b) * SHM_V + vst1) = sr_[i].vs1; \
;     _Pragma("unroll") for (int q_ = 0; q_ < KPT; ++q_) *(bf16x8*)(K_lds + (b) * SHM_K + kst[q_]) = sr_[i].ks[q_]; } while (0)
; #define RESC(a) do { if constexpr (!FIXM) if (__any((a) < 1.f)) { if (hi == 0) al_l[r32] = (a); asm volatile("s_waitcnt lgkmcnt(0)" ::: "memory"); \
;     _Pragma("unroll") for (int d = 0; d < 4; ++d) _Pragma("unroll") for (int r = 0; r < 16; ++r) o[d][r] *= al_l[crow(r, hi)]; } } while (0)
;     ...
;       constexpr bool LATE = (DQK == 128) ? ((ATT_STAGE_LATE & 2) != 0) : ((ATT_STAGE_LATE & 4) != 0);
;       if constexpr (!LATE) { if (j + 1 < nt) { SWRITE(b ^ 1, 0); } if (j + 2 < nt) { SLOAD(0, (j + 2) * KVBLK); } }
;       SBAR(); qkt<DQK>(pA0, pA1, K_lds + b * SHM_K, qr, r32, hi); SBAR();
;       if constexpr (LATE) { if (j + 1 < nt) { SWRITE(b ^ 1, 0); } if (j + 2 < nt) { SLOAD(0, (j + 2) * KVBLK); } SBAR(); }
;       }
;       const int vb = vb0 + b * SHM_V;
;       if constexpr (DQK != 192) {
;         VF f0, f1; v_issue<0>(f0, vb);
;         partialSM<FIXM>(pA0, pA1, m_reg, mnA, alA, C, thrS, kb0 + j * KVBLK, hi);
;         RESC(alA);
;         finishSM<FIXM>(pA0, pA1, alA, l_reg, pa0, pa1, pa2, pa3, kb0 + j * KVBLK, hi); SBAR();
;         pv_pipe(o, vb, f0, f1, pa0, pa1, pa2, pa3);
;       } else {
;         partialSM<FIXM>(pA0, pA1, m_reg, mnA, alA, C, thrS, kb0 + j * KVBLK, hi);
;         RESC(alA);
;         finishSM<FIXM>(pA0, pA1, alA, l_reg, pa0, pa1, pa2, pa3, kb0 + j * KVBLK, hi); SBAR();
;         pv_d0(o, vb, pa0, pa1, pa2, pa3);
	s_add_i32 s1, 0, 0x16000
	v_add3_u32 v68, s1, v224, v189
	ds_read_b128 v[64:67], v68
	v_add3_u32 v176, s1, v223, v189
	ds_read_b128 v[172:175], v176
	s_waitcnt lgkmcnt(1)
	v_mfma_f32_32x32x16_bf16 v[80:95], v[64:67], v[144:147], 0
	ds_read_b128 v[64:67], v68 offset:12288
	s_waitcnt lgkmcnt(1)
	v_mfma_f32_32x32x16_bf16 v[80:95], v[172:175], v[140:143], v[80:95]
	ds_read_b128 v[172:175], v176 offset:12288
	v_add3_u32 v176, s1, v222, v189
	s_waitcnt lgkmcnt(1)
	v_mfma_f32_32x32x16_bf16 v[64:79], v[64:67], v[144:147], 0
	s_waitcnt lgkmcnt(0)
	v_mfma_f32_32x32x16_bf16 v[64:79], v[172:175], v[140:143], v[64:79]
	ds_read_b128 v[172:175], v176
	s_waitcnt lgkmcnt(0)
	v_mfma_f32_32x32x16_bf16 v[80:95], v[172:175], v[136:139], v[80:95]
	ds_read_b128 v[172:175], v176 offset:12288
	v_add3_u32 v176, s1, v221, v189
	s_waitcnt lgkmcnt(0)
	v_mfma_f32_32x32x16_bf16 v[64:79], v[172:175], v[136:139], v[64:79]
	ds_read_b128 v[172:175], v176
	s_waitcnt lgkmcnt(0)
	v_mfma_f32_32x32x16_bf16 v[80:95], v[172:175], v[132:135], v[80:95]
	ds_read_b128 v[172:175], v176 offset:12288
	v_add3_u32 v176, s1, v220, v189
	s_waitcnt lgkmcnt(0)
	v_mfma_f32_32x32x16_bf16 v[64:79], v[172:175], v[132:135], v[64:79]
	ds_read_b128 v[172:175], v176
	s_waitcnt lgkmcnt(0)
	v_mfma_f32_32x32x16_bf16 v[80:95], v[172:175], v[128:131], v[80:95]
	ds_read_b128 v[172:175], v176 offset:12288
	v_add3_u32 v176, s1, v219, v189
	s_waitcnt lgkmcnt(0)
	v_mfma_f32_32x32x16_bf16 v[64:79], v[172:175], v[128:131], v[64:79]
	ds_read_b128 v[172:175], v176
	s_waitcnt lgkmcnt(0)
	v_mfma_f32_32x32x16_bf16 v[80:95], v[172:175], v[124:127], v[80:95]
	ds_read_b128 v[172:175], v176 offset:12288
	v_add3_u32 v176, s1, v218, v189
	s_waitcnt lgkmcnt(0)
	v_mfma_f32_32x32x16_bf16 v[64:79], v[172:175], v[124:127], v[64:79]
	ds_read_b128 v[172:175], v176
	s_waitcnt lgkmcnt(0)
	v_mfma_f32_32x32x16_bf16 v[80:95], v[172:175], v[120:123], v[80:95]
	ds_read_b128 v[172:175], v176 offset:12288
	v_add3_u32 v176, s1, v217, v189
	s_waitcnt lgkmcnt(0)
	v_mfma_f32_32x32x16_bf16 v[64:79], v[172:175], v[120:123], v[64:79]
	ds_read_b128 v[172:175], v176
	s_waitcnt lgkmcnt(0)
	v_mfma_f32_32x32x16_bf16 v[80:95], v[172:175], v[116:119], v[80:95]
	ds_read_b128 v[172:175], v176 offset:12288
	v_add3_u32 v176, s1, v216, v189
	s_waitcnt lgkmcnt(0)
	v_mfma_f32_32x32x16_bf16 v[64:79], v[172:175], v[116:119], v[64:79]
	ds_read_b128 v[172:175], v176
	s_waitcnt lgkmcnt(0)
	v_mfma_f32_32x32x16_bf16 v[80:95], v[172:175], v[112:115], v[80:95]
	ds_read_b128 v[172:175], v176 offset:12288
	v_add3_u32 v176, s1, v215, v189
	s_waitcnt lgkmcnt(0)
	v_mfma_f32_32x32x16_bf16 v[64:79], v[172:175], v[112:115], v[64:79]
	ds_read_b128 v[172:175], v176
	s_waitcnt lgkmcnt(0)
	v_mfma_f32_32x32x16_bf16 v[80:95], v[172:175], v[108:111], v[80:95]
	ds_read_b128 v[172:175], v176 offset:12288
	v_add3_u32 v176, s1, v214, v189
	s_waitcnt lgkmcnt(0)
	v_mfma_f32_32x32x16_bf16 v[64:79], v[172:175], v[108:111], v[64:79]
	ds_read_b128 v[172:175], v176
	s_waitcnt lgkmcnt(0)
	v_mfma_f32_32x32x16_bf16 v[80:95], v[172:175], v[104:107], v[80:95]
	ds_read_b128 v[172:175], v176 offset:12288
	v_add3_u32 v176, s1, v191, v189
	s_waitcnt lgkmcnt(0)
	v_mfma_f32_32x32x16_bf16 v[64:79], v[172:175], v[104:107], v[64:79]
	ds_read_b128 v[172:175], v176
	s_waitcnt lgkmcnt(0)
	v_mfma_f32_32x32x16_bf16 v[80:95], v[172:175], v[100:103], v[80:95]
	ds_read_b128 v[172:175], v176 offset:12288
	s_waitcnt lgkmcnt(0)
	v_mfma_f32_32x32x16_bf16 v[64:79], v[172:175], v[100:103], v[64:79]
	s_waitcnt vmcnt(4)
	ds_write_b128 v231, v[152:155]
	s_waitcnt vmcnt(3)
	ds_write_b128 v232, v[148:151]
	s_waitcnt vmcnt(2)
	ds_write_b128 v233, v[164:167]
	s_waitcnt vmcnt(1)
	ds_write_b128 v234, v[160:163]
	s_waitcnt vmcnt(0)
	ds_write_b128 v235, v[156:159]
	v_exp_f32_e32 v80, v80
	v_exp_f32_e32 v81, v81
	v_exp_f32_e32 v82, v82
	v_exp_f32_e32 v83, v83
	v_exp_f32_e32 v84, v84
	v_exp_f32_e32 v149, v64
	v_add_f32_e32 v64, 0, v80
	v_exp_f32_e32 v85, v85
	v_add_f32_e32 v64, v81, v64
	v_exp_f32_e32 v86, v86
	v_add_f32_e32 v64, v82, v64
	v_exp_f32_e32 v87, v87
	v_add_f32_e32 v64, v83, v64
	v_exp_f32_e32 v88, v88
	v_add_f32_e32 v64, v84, v64
	v_exp_f32_e32 v89, v89
	v_add_f32_e32 v64, v85, v64
	v_exp_f32_e32 v90, v90
	v_add_f32_e32 v64, v86, v64
	v_exp_f32_e32 v91, v91
	v_add_f32_e32 v64, v87, v64
	v_exp_f32_e32 v92, v92
	v_add_f32_e32 v64, v88, v64
	v_exp_f32_e32 v93, v93
	v_add_f32_e32 v64, v89, v64
	v_exp_f32_e32 v94, v94
	v_add_f32_e32 v64, v90, v64
	v_exp_f32_e32 v95, v95
	v_add_f32_e32 v64, v91, v64
	v_add_f32_e32 v64, v92, v64
	v_exp_f32_e32 v150, v65
	v_add_f32_e32 v64, v93, v64
	v_exp_f32_e32 v151, v66
	v_add_f32_e32 v64, v94, v64
	v_exp_f32_e32 v152, v67
	v_add_f32_e32 v64, v95, v64
	v_exp_f32_e32 v153, v68
	v_add_f32_e32 v64, v149, v64
	v_exp_f32_e32 v154, v69
	v_add_f32_e32 v64, v150, v64
	v_exp_f32_e32 v155, v70
	v_add_f32_e32 v64, v151, v64
	v_exp_f32_e32 v156, v71
	v_add_f32_e32 v64, v152, v64
	v_exp_f32_e32 v157, v72
	v_add_f32_e32 v64, v153, v64
	v_exp_f32_e32 v158, v73
	v_add_f32_e32 v64, v154, v64
	v_exp_f32_e32 v159, v74
	v_add_f32_e32 v64, v155, v64
	v_exp_f32_e32 v160, v75
	v_add_f32_e32 v64, v156, v64
	v_exp_f32_e32 v161, v76
	v_add_f32_e32 v64, v157, v64
	v_exp_f32_e32 v162, v77
	v_add_f32_e32 v64, v158, v64
	v_exp_f32_e32 v163, v78
	v_add_f32_e32 v64, v159, v64
	v_exp_f32_e32 v79, v79
	v_add_f32_e32 v64, v160, v64
	v_add_f32_e32 v64, v161, v64
	v_add_f32_e32 v64, v162, v64
	v_add_f32_e32 v64, v163, v64
	v_add_f32_e32 v64, v79, v64
	v_add_u32_e32 v148, 0x4000, v187
	v_add_f32_e32 v164, v230, v64
	v_cvt_pk_bf16_f32 v64, v80, v81
	v_cvt_pk_bf16_f32 v65, v82, v83
	v_cvt_pk_bf16_f32 v66, v84, v85
	v_cvt_pk_bf16_f32 v67, v86, v87
	v_cvt_pk_bf16_f32 v68, v88, v89
	v_cvt_pk_bf16_f32 v69, v90, v91
	v_cvt_pk_bf16_f32 v70, v92, v93
	v_cvt_pk_bf16_f32 v71, v94, v95
	v_cvt_pk_bf16_f32 v72, v149, v150
	v_cvt_pk_bf16_f32 v73, v151, v152
	v_cvt_pk_bf16_f32 v74, v153, v154
	v_cvt_pk_bf16_f32 v75, v155, v156
	v_cvt_pk_bf16_f32 v76, v157, v158
	v_cvt_pk_bf16_f32 v77, v159, v160
	v_cvt_pk_bf16_f32 v78, v161, v162
	v_cvt_pk_bf16_f32 v79, v163, v79
	ds_read_b64_tr_b16 v[80:81], v148 offset:0
	ds_read_b64_tr_b16 v[82:83], v148 offset:0x800
	ds_read_b64_tr_b16 v[84:85], v148 offset:0x1000
	ds_read_b64_tr_b16 v[86:87], v148 offset:0x1800
	ds_read_b64_tr_b16 v[88:89], v148 offset:0x2000
	ds_read_b64_tr_b16 v[90:91], v148 offset:0x2800
	ds_read_b64_tr_b16 v[92:93], v148 offset:0x3000
	ds_read_b64_tr_b16 v[94:95], v148 offset:0x3800
	s_waitcnt lgkmcnt(0)
; #define SBAR() __builtin_amdgcn_sched_barrier(0)
; __device__ __forceinline__ int crow(int r, int hi) { return (r & 3) + 8 * (r >> 2) + 4 * hi; }
; #define SLOAD(i, k0) do { const int sv_ = (k0) * (ldv * 2), sk_ = (k0) * (ldk * 2); sr_[i].vs0 = BLD(rsV, vg0 * 2, sv_); sr_[i].vs1 = BLD(rsV, vg1 * 2, sv_); \
;     _Pragma("unroll") for (int q_ = 0; q_ < KPT; ++q_) sr_[i].ks[q_] = BLD(rsK, kg[q_] * 2, sk_); } while (0)
; #define SWRITE(b, i) do { *(bf16x8*)(V_lds + (b) * SHM_V + vst0) = sr_[i].vs0; *(bf16x8*)(V_lds + (b) * SHM_V + vst1) = sr_[i].vs1; \
;     _Pragma("unroll") for (int q_ = 0; q_ < KPT; ++q_) *(bf16x8*)(K_lds + (b) * SHM_K + kst[q_]) = sr_[i].ks[q_]; } while (0)
; #define RESC(a) do { if constexpr (!FIXM) if (__any((a) < 1.f)) { if (hi == 0) al_l[r32] = (a); asm volatile("s_waitcnt lgkmcnt(0)" ::: "memory"); \
;     _Pragma("unroll") for (int d = 0; d < 4; ++d) _Pragma("unroll") for (int r = 0; r < 16; ++r) o[d][r] *= al_l[crow(r, hi)]; } } while (0)
; template <bool FIXM>
; __device__ __forceinline__ void partialSM(f32x16& p0, f32x16& p1, float& m_reg, float& mn, float& alpha, const float C, const float thrS, const int kb, const int hi) {
;     ...
;     if (kb + KVBLK > LROWS) {
; #pragma unroll
;       for (int r = 0; r < 16; ++r) { if (kb + crow(r, hi) >= LROWS) p0[r] = 0.f; }
;     }
;     ...
;       constexpr bool LATE = (DQK == 128) ? ((ATT_STAGE_LATE & 2) != 0) : ((ATT_STAGE_LATE & 4) != 0);
;       if constexpr (!LATE) { if (j + 1 < nt) { SWRITE(b ^ 1, 0); } if (j + 2 < nt) { SLOAD(0, (j + 2) * KVBLK); } }
;       SBAR(); qkt<DQK>(pA0, pA1, K_lds + b * SHM_K, qr, r32, hi); SBAR();
;       if constexpr (LATE) { if (j + 1 < nt) { SWRITE(b ^ 1, 0); } if (j + 2 < nt) { SLOAD(0, (j + 2) * KVBLK); } SBAR(); }
;       }
;       const int vb = vb0 + b * SHM_V;
;       if constexpr (DQK != 192) {
;         VF f0, f1; v_issue<0>(f0, vb);
;         partialSM<FIXM>(pA0, pA1, m_reg, mnA, alA, C, thrS, kb0 + j * KVBLK, hi);
;         RESC(alA);
;         finishSM<FIXM>(pA0, pA1, alA, l_reg, pa0, pa1, pa2, pa3, kb0 + j * KVBLK, hi); SBAR();
;         pv_pipe(o, vb, f0, f1, pa0, pa1, pa2, pa3);
;       } else {
;         partialSM<FIXM>(pA0, pA1, m_reg, mnA, alA, C, thrS, kb0 + j * KVBLK, hi);
;         RESC(alA);
;         finishSM<FIXM>(pA0, pA1, alA, l_reg, pa0, pa1, pa2, pa3, kb0 + j * KVBLK, hi); SBAR();
;         pv_d0(o, vb, pa0, pa1, pa2, pa3);
	s_nop 0
	v_mfma_f32_32x32x16_bf16 v[48:63], v[64:67], v[80:83], v[48:63]
	ds_read_b64_tr_b16 v[80:81], v148 offset:0x200
	ds_read_b64_tr_b16 v[82:83], v148 offset:0xa00
	v_mfma_f32_32x32x16_bf16 v[48:63], v[68:71], v[84:87], v[48:63]
	ds_read_b64_tr_b16 v[84:85], v148 offset:0x1200
	ds_read_b64_tr_b16 v[86:87], v148 offset:0x1a00
	v_mfma_f32_32x32x16_bf16 v[48:63], v[72:75], v[88:91], v[48:63]
	ds_read_b64_tr_b16 v[88:89], v148 offset:0x2200
	ds_read_b64_tr_b16 v[90:91], v148 offset:0x2a00
	v_mfma_f32_32x32x16_bf16 v[48:63], v[76:79], v[92:95], v[48:63]
	ds_read_b64_tr_b16 v[92:93], v148 offset:0x3200
	ds_read_b64_tr_b16 v[94:95], v148 offset:0x3a00
	s_waitcnt lgkmcnt(0)
	v_mfma_f32_32x32x16_bf16 v[32:47], v[64:67], v[80:83], v[32:47]
	ds_read_b64_tr_b16 v[80:81], v148 offset:0x400
	ds_read_b64_tr_b16 v[82:83], v148 offset:0xc00
	v_mfma_f32_32x32x16_bf16 v[32:47], v[68:71], v[84:87], v[32:47]
	ds_read_b64_tr_b16 v[84:85], v148 offset:0x1400
	ds_read_b64_tr_b16 v[86:87], v148 offset:0x1c00
	v_mfma_f32_32x32x16_bf16 v[32:47], v[72:75], v[88:91], v[32:47]
	ds_read_b64_tr_b16 v[88:89], v148 offset:0x2400
	ds_read_b64_tr_b16 v[90:91], v148 offset:0x2c00
	v_mfma_f32_32x32x16_bf16 v[32:47], v[76:79], v[92:95], v[32:47]
	ds_read_b64_tr_b16 v[92:93], v148 offset:0x3400
	ds_read_b64_tr_b16 v[94:95], v148 offset:0x3c00
	s_waitcnt lgkmcnt(0)
	v_mfma_f32_32x32x16_bf16 v[16:31], v[64:67], v[80:83], v[16:31]
	ds_read_b64_tr_b16 v[80:81], v148 offset:0x600
	ds_read_b64_tr_b16 v[82:83], v148 offset:0xe00
	v_mfma_f32_32x32x16_bf16 v[16:31], v[68:71], v[84:87], v[16:31]
	ds_read_b64_tr_b16 v[84:85], v148 offset:0x1600
	ds_read_b64_tr_b16 v[86:87], v148 offset:0x1e00
	v_mfma_f32_32x32x16_bf16 v[16:31], v[72:75], v[88:91], v[16:31]
	ds_read_b64_tr_b16 v[88:89], v148 offset:0x2600
	ds_read_b64_tr_b16 v[90:91], v148 offset:0x2e00
	v_mfma_f32_32x32x16_bf16 v[16:31], v[76:79], v[92:95], v[16:31]
	ds_read_b64_tr_b16 v[92:93], v148 offset:0x3600
	ds_read_b64_tr_b16 v[94:95], v148 offset:0x3e00
	s_waitcnt lgkmcnt(0)
	v_mfma_f32_32x32x16_bf16 v[0:15], v[64:67], v[80:83], v[0:15]
	v_and_b32_e32 v148, 0x3fffffc0, v213
	s_waitcnt lgkmcnt(0)
	s_barrier
	v_mfma_f32_32x32x16_bf16 v[0:15], v[68:71], v[84:87], v[0:15]
	v_mfma_f32_32x32x16_bf16 v[0:15], v[72:75], v[88:91], v[0:15]
	v_mfma_f32_32x32x16_bf16 v[0:15], v[76:79], v[92:95], v[0:15]
	v_add3_u32 v64, s0, v224, v189
	ds_read_b128 v[64:67], v64
	v_add3_u32 v80, s0, v223, v189
	ds_read_b128 v[80:83], v80
	s_waitcnt lgkmcnt(1)
	v_mfma_f32_32x32x16_bf16 v[64:79], v[64:67], v[144:147], 0
	s_waitcnt lgkmcnt(0)
	v_mfma_f32_32x32x16_bf16 v[64:79], v[80:83], v[140:143], v[64:79]
	v_add3_u32 v80, s0, v222, v189
	ds_read_b128 v[80:83], v80
	s_waitcnt lgkmcnt(0)
	v_mfma_f32_32x32x16_bf16 v[64:79], v[80:83], v[136:139], v[64:79]
	v_add3_u32 v80, s0, v221, v189
	ds_read_b128 v[80:83], v80
	s_waitcnt lgkmcnt(0)
	v_mfma_f32_32x32x16_bf16 v[64:79], v[80:83], v[132:135], v[64:79]
	v_add3_u32 v80, s0, v220, v189
	ds_read_b128 v[80:83], v80
	s_waitcnt lgkmcnt(0)
	v_mfma_f32_32x32x16_bf16 v[64:79], v[80:83], v[128:131], v[64:79]
	v_add3_u32 v80, s0, v219, v189
	ds_read_b128 v[80:83], v80
	s_waitcnt lgkmcnt(0)
	v_mfma_f32_32x32x16_bf16 v[64:79], v[80:83], v[124:127], v[64:79]
	v_add3_u32 v80, s0, v218, v189
	ds_read_b128 v[80:83], v80
	s_waitcnt lgkmcnt(0)
	v_mfma_f32_32x32x16_bf16 v[64:79], v[80:83], v[120:123], v[64:79]
	v_add3_u32 v80, s0, v217, v189
	ds_read_b128 v[80:83], v80
	s_waitcnt lgkmcnt(0)
	v_mfma_f32_32x32x16_bf16 v[64:79], v[80:83], v[116:119], v[64:79]
	v_add3_u32 v80, s0, v216, v189
	ds_read_b128 v[80:83], v80
	s_waitcnt lgkmcnt(0)
	v_mfma_f32_32x32x16_bf16 v[64:79], v[80:83], v[112:115], v[64:79]
	v_add3_u32 v80, s0, v215, v189
	ds_read_b128 v[80:83], v80
	s_waitcnt lgkmcnt(0)
	v_mfma_f32_32x32x16_bf16 v[64:79], v[80:83], v[108:111], v[64:79]
	v_add3_u32 v80, s0, v214, v189
	ds_read_b128 v[80:83], v80
	s_waitcnt lgkmcnt(0)
	v_mfma_f32_32x32x16_bf16 v[64:79], v[80:83], v[104:107], v[64:79]
	v_add3_u32 v80, s0, v191, v189
	ds_read_b128 v[80:83], v80
	s_waitcnt lgkmcnt(0)
	v_mfma_f32_32x32x16_bf16 v[64:79], v[80:83], v[100:103], v[64:79]
	s_nop 11
	v_exp_f32_e32 v72, v64
	v_exp_f32_e32 v65, v65
	v_exp_f32_e32 v73, v66
	v_exp_f32_e32 v67, v67
	v_exp_f32_e32 v68, v68
	v_add_f32_e32 v64, 0, v72
	v_exp_f32_e32 v69, v69
	v_add_f32_e32 v64, v65, v64
	v_exp_f32_e32 v70, v70
	v_add_f32_e32 v64, v73, v64
	v_exp_f32_e32 v71, v71
	v_add_f32_e32 v64, v67, v64
	v_add_f32_e32 v64, v68, v64
	v_add_f32_e32 v64, v69, v64
	v_add_f32_e32 v64, v70, v64
	v_add_f32_e32 v64, v71, v64
	v_add_f32_e32 v64, 0, v64
	v_add_f32_e32 v64, v164, v64
	v_cvt_pk_bf16_f32 v66, v72, v65
	v_cvt_pk_bf16_f32 v67, v73, v67
	v_cvt_pk_bf16_f32 v68, v68, v69
	v_cvt_pk_bf16_f32 v69, v70, v71
	v_cvt_pk_bf16_f32 v70, v169, v169
	v_cvt_pk_bf16_f32 v71, v169, v169
	v_cvt_pk_bf16_f32 v72, v169, v169
	v_cvt_pk_bf16_f32 v73, v169, v169
	v_cvt_pk_bf16_f32 v74, v169, v169
	v_cvt_pk_bf16_f32 v75, v169, v169
	v_cvt_pk_bf16_f32 v76, v169, v169
	v_cvt_pk_bf16_f32 v77, v169, v169
	v_cvt_pk_bf16_f32 v78, v169, v169
	v_cvt_pk_bf16_f32 v79, v169, v169
	v_cvt_pk_bf16_f32 v80, v169, v169
	v_cvt_pk_bf16_f32 v81, v169, v169
	ds_read_b64_tr_b16 v[82:83], v187 offset:0
	ds_read_b64_tr_b16 v[84:85], v187 offset:0x800
	ds_read_b64_tr_b16 v[86:87], v187 offset:0x1000
	ds_read_b64_tr_b16 v[88:89], v187 offset:0x1800
	ds_read_b64_tr_b16 v[90:91], v187 offset:0x2000
	ds_read_b64_tr_b16 v[92:93], v187 offset:0x2800
	ds_read_b64_tr_b16 v[100:101], v187 offset:0x3000
	ds_read_b64_tr_b16 v[102:103], v187 offset:0x3800
	s_waitcnt lgkmcnt(0)
; __device__ __forceinline__ int crow(int r, int hi) { return (r & 3) + 8 * (r >> 2) + 4 * hi; }
; __device__ __forceinline__ float bf2f(unsigned short b) { return __uint_as_float((unsigned)b << 16); }
; __device__ __forceinline__ unsigned f2bf(float f) { unsigned u = __float_as_uint(f); return (u + 0x7fffu + ((u >> 16) & 1u)) >> 16; }
; __device__ __forceinline__ float bf2f(unsigned short b) { return __uint_as_float((unsigned)b << 16); }
; __device__ __forceinline__ unsigned f2bf(float f) { unsigned u = __float_as_uint(f); return (u + 0x7fffu + ((u >> 16) & 1u)) >> 16; }
;     ...
;   { auto rr = __builtin_amdgcn_permlane32_swap(__float_as_uint(l_reg), __float_as_uint(l_reg), false, false);
;     l_reg = __uint_as_float(rr[0]) + __uint_as_float(rr[1]); }
;   if constexpr (SPLIT) if (part != nullptr) {
;     if (wid == 0) {
; #pragma unroll
;       for (int r = 0; r < 16; ++r) { const int orow = crow(r, hi);
;         if (orow < 16) {
; #pragma unroll
;           for (int d0 = 0; d0 < 4; ++d0) part[orow * 132 + d0 * 32 + r32] = o[d0][r]; } }
;       if (hi == 0 && r32 < 16) { part[r32 * 132 + 128] = m_reg; part[r32 * 132 + 129] = l_reg; }
;     }
;     __syncthreads();
;     return;
;   }
;   if (hi == 0) li_l[r32] = l_reg; asm volatile("s_waitcnt lgkmcnt(0)" ::: "memory");
; #pragma unroll
;   for (int r = 0; r < 16; ++r) { const int orow = wid * QBLK + crow(r, hi); const float rli = __builtin_amdgcn_rcpf(li_l[crow(r, hi)]);
;     if (orow < nvalid) {
;       if constexpr (MODE == 0) {
; #pragma unroll
;         for (int d0 = 0; d0 < 4; ++d0) Of[(long)orow * ldo + d0 * 32 + r32] = o[d0][r] * rli;
;       } else {
; #pragma unroll
;         for (int d0 = 0; d0 < 4; ++d0) { const float g = bf2f(Gb[(long)orow * ldg + d0 * 32 + r32]); const float sg = g / (1.f + __expf(-g));
;           Yb[(long)orow * ldy + d0 * 32 + r32] = (bf16)f2bf(o[d0][r] * rli * sg); }
	s_nop 0
	v_mfma_f32_32x32x16_bf16 v[48:63], v[66:69], v[82:85], v[48:63]
	ds_read_b64_tr_b16 v[82:83], v187 offset:0x200
	ds_read_b64_tr_b16 v[84:85], v187 offset:0xa00
	v_mfma_f32_32x32x16_bf16 v[48:63], v[70:73], v[86:89], v[48:63]
	ds_read_b64_tr_b16 v[86:87], v187 offset:0x1200
	ds_read_b64_tr_b16 v[88:89], v187 offset:0x1a00
	v_mfma_f32_32x32x16_bf16 v[48:63], v[74:77], v[90:93], v[48:63]
	ds_read_b64_tr_b16 v[90:91], v187 offset:0x2200
	ds_read_b64_tr_b16 v[92:93], v187 offset:0x2a00
	v_mfma_f32_32x32x16_bf16 v[48:63], v[78:81], v[100:103], v[48:63]
	ds_read_b64_tr_b16 v[100:101], v187 offset:0x3200
	ds_read_b64_tr_b16 v[102:103], v187 offset:0x3a00
	s_waitcnt lgkmcnt(0)
	v_mfma_f32_32x32x16_bf16 v[32:47], v[66:69], v[82:85], v[32:47]
	ds_read_b64_tr_b16 v[82:83], v187 offset:0x400
	ds_read_b64_tr_b16 v[84:85], v187 offset:0xc00
	v_mfma_f32_32x32x16_bf16 v[32:47], v[70:73], v[86:89], v[32:47]
	ds_read_b64_tr_b16 v[86:87], v187 offset:0x1400
	ds_read_b64_tr_b16 v[88:89], v187 offset:0x1c00
	v_mfma_f32_32x32x16_bf16 v[32:47], v[74:77], v[90:93], v[32:47]
	ds_read_b64_tr_b16 v[90:91], v187 offset:0x2400
	ds_read_b64_tr_b16 v[92:93], v187 offset:0x2c00
	v_mfma_f32_32x32x16_bf16 v[32:47], v[78:81], v[100:103], v[32:47]
	ds_read_b64_tr_b16 v[100:101], v187 offset:0x3400
	ds_read_b64_tr_b16 v[102:103], v187 offset:0x3c00
	s_waitcnt lgkmcnt(0)
	v_mfma_f32_32x32x16_bf16 v[16:31], v[66:69], v[82:85], v[16:31]
	ds_read_b64_tr_b16 v[82:83], v187 offset:0x600
	ds_read_b64_tr_b16 v[84:85], v187 offset:0xe00
	v_mfma_f32_32x32x16_bf16 v[16:31], v[70:73], v[86:89], v[16:31]
	ds_read_b64_tr_b16 v[86:87], v187 offset:0x1600
	ds_read_b64_tr_b16 v[88:89], v187 offset:0x1e00
	v_mfma_f32_32x32x16_bf16 v[16:31], v[74:77], v[90:93], v[16:31]
	ds_read_b64_tr_b16 v[90:91], v187 offset:0x2600
	ds_read_b64_tr_b16 v[92:93], v187 offset:0x2e00
	v_mfma_f32_32x32x16_bf16 v[16:31], v[78:81], v[100:103], v[16:31]
	ds_read_b64_tr_b16 v[100:101], v187 offset:0x3600
	ds_read_b64_tr_b16 v[102:103], v187 offset:0x3e00
	s_waitcnt lgkmcnt(0)
	v_mfma_f32_32x32x16_bf16 v[0:15], v[66:69], v[82:85], v[0:15]
	s_add_i32 s0, 0, 0x20000
	v_mov_b32_e32 v65, v64
	v_lshl_add_u32 v69, v148, 2, s0
	s_nop 0
	v_permlane32_swap_b32_e32 v64, v65
	v_cmp_gt_u32_e32 vcc, 32, v195
	v_mfma_f32_32x32x16_bf16 v[0:15], v[70:73], v[86:89], v[0:15]
	v_mfma_f32_32x32x16_bf16 v[0:15], v[74:77], v[90:93], v[0:15]
	v_mfma_f32_32x32x16_bf16 v[0:15], v[78:81], v[100:103], v[0:15]
	s_and_saveexec_b64 s[0:1], vcc
	v_lshl_add_u32 v66, v193, 2, v69
	v_add_f32_e32 v64, v64, v65
	ds_write_b32 v66, v64
	s_or_b64 exec, exec, s[0:1]
	s_lshl_b64 s[0:1], s[4:5], 12
	s_lshl_b32 s2, s97, 7
	s_mul_i32 s6, s4, 0x2e00
	s_mul_hi_u32 s3, s4, 0x2e00
	s_add_u32 s6, s10, s6
	s_addc_u32 s7, s11, s3
	v_readlane_b32 s18, v252, 49
	v_readlane_b32 s19, v252, 50
	s_add_u32 s12, s18, s0
	s_addc_u32 s18, s19, s1
	s_ashr_i32 s3, s2, 31
	s_lshl_b64 s[0:1], s[2:3], 1
	s_add_u32 s2, s12, s0
	s_addc_u32 s3, s18, s1
	s_add_u32 s0, s6, s0
	s_addc_u32 s1, s7, s1
	s_waitcnt lgkmcnt(0)
	v_lshlrev_b32_e32 v72, 2, v194
	v_lshlrev_b32_e32 v64, 1, v193
	v_mov_b32_e32 v65, v169
	v_lshl_add_u64 v[66:67], s[0:1], 0, v[64:65]
	s_mov_b64 s[0:1], 0x2180
	v_or_b32_e32 v68, v72, v192
	v_lshl_add_u64 v[66:67], v[66:67], 0, s[0:1]
	v_lshl_add_u64 v[64:65], s[2:3], 0, v[64:65]
	v_cmp_gt_i32_e32 vcc, s96, v68
	v_lshl_add_u32 v73, v72, 2, v69
	s_and_saveexec_b64 s[0:1], vcc
	s_cbranch_execz .LBB0_583
	v_mad_i64_i32 v[70:71], s[2:3], v68, s20, v[66:67]
	global_load_ushort v75, v[70:71], off
	global_load_ushort v100, v[70:71], off offset:64
	global_load_ushort v101, v[70:71], off offset:128
	global_load_ushort v102, v[70:71], off offset:192
	ds_read_b32 v69, v73
	s_waitcnt lgkmcnt(0)
	v_rcp_f32_e32 v74, v69
	v_ashrrev_i32_e32 v69, 31, v68
	v_lshlrev_b64 v[68:69], 12, v[68:69]
	v_lshl_add_u64 v[68:69], v[64:65], 0, v[68:69]
	v_mul_f32_e32 v48, v48, v74
	v_mul_f32_e32 v32, v32, v74
	v_mul_f32_e32 v16, v16, v74
	v_mul_f32_e32 v0, v0, v74
	s_waitcnt vmcnt(0)
	v_lshlrev_b32_e32 v75, 16, v75
	v_mul_f32_e32 v76, 0xbfb8aa3b, v75
	v_exp_f32_e32 v76, v76
	s_nop 0
	v_add_f32_e32 v76, 1.0, v76
	v_div_scale_f32 v77, s[2:3], v76, v76, v75
	v_rcp_f32_e32 v78, v77
	s_nop 0
	v_fma_f32 v79, -v77, v78, 1.0
	v_fmac_f32_e32 v78, v79, v78
	v_div_scale_f32 v79, vcc, v75, v76, v75
	v_mul_f32_e32 v80, v79, v78
	v_fma_f32 v81, -v77, v80, v79
	v_fmac_f32_e32 v80, v81, v78
	v_fma_f32 v77, -v77, v80, v79
	v_div_fmas_f32 v77, v77, v78, v80
	v_div_fixup_f32 v75, v77, v76, v75
	v_mul_f32_e32 v48, v48, v75
	v_bfe_u32 v75, v48, 16, 1
	v_add3_u32 v48, v48, v75, s15
	global_store_short_d16_hi v[68:69], v48, off offset:2048


; __device__ __forceinline__ float bf2f(unsigned short b) { return __uint_as_float((unsigned)b << 16); }
; __device__ __forceinline__ unsigned f2bf(float f) { unsigned u = __float_as_uint(f); return (u + 0x7fffu + ((u >> 16) & 1u)) >> 16; }
; __device__ __forceinline__ float bf2f(unsigned short b) { return __uint_as_float((unsigned)b << 16); }
; __device__ __forceinline__ unsigned f2bf(float f) { unsigned u = __float_as_uint(f); return (u + 0x7fffu + ((u >> 16) & 1u)) >> 16; }
;     ...
;         for (int d0 = 0; d0 < 4; ++d0) { const float g = bf2f(Gb[(long)orow * ldg + d0 * 32 + r32]); const float sg = g / (1.f + __expf(-g));
;           Yb[(long)orow * ldy + d0 * 32 + r32] = (bf16)f2bf(o[d0][r] * rli * sg); }
	v_lshlrev_b32_e32 v48, 16, v100
	v_mul_f32_e32 v75, 0xbfb8aa3b, v48
	v_exp_f32_e32 v75, v75
	s_nop 0
	v_add_f32_e32 v75, 1.0, v75
	v_div_scale_f32 v76, s[2:3], v75, v75, v48
	v_rcp_f32_e32 v77, v76
	s_nop 0
	v_fma_f32 v78, -v76, v77, 1.0
	v_fmac_f32_e32 v77, v78, v77
	v_div_scale_f32 v78, vcc, v48, v75, v48
	v_mul_f32_e32 v79, v78, v77
	v_fma_f32 v80, -v76, v79, v78
	v_fmac_f32_e32 v79, v80, v77
	v_fma_f32 v76, -v76, v79, v78
	v_div_fmas_f32 v76, v76, v77, v79
	v_div_fixup_f32 v48, v76, v75, v48
	v_mul_f32_e32 v32, v32, v48
	v_bfe_u32 v48, v32, 16, 1
	v_add3_u32 v32, v32, v48, s15
	global_store_short_d16_hi v[68:69], v32, off offset:2112


; __device__ __forceinline__ float bf2f(unsigned short b) { return __uint_as_float((unsigned)b << 16); }
; __device__ __forceinline__ unsigned f2bf(float f) { unsigned u = __float_as_uint(f); return (u + 0x7fffu + ((u >> 16) & 1u)) >> 16; }
; __device__ __forceinline__ float bf2f(unsigned short b) { return __uint_as_float((unsigned)b << 16); }
; __device__ __forceinline__ unsigned f2bf(float f) { unsigned u = __float_as_uint(f); return (u + 0x7fffu + ((u >> 16) & 1u)) >> 16; }
;     ...
;         for (int d0 = 0; d0 < 4; ++d0) { const float g = bf2f(Gb[(long)orow * ldg + d0 * 32 + r32]); const float sg = g / (1.f + __expf(-g));
;           Yb[(long)orow * ldy + d0 * 32 + r32] = (bf16)f2bf(o[d0][r] * rli * sg); }
	v_lshlrev_b32_e32 v32, 16, v101
	v_mul_f32_e32 v48, 0xbfb8aa3b, v32
	v_exp_f32_e32 v48, v48
	s_nop 0
	v_add_f32_e32 v48, 1.0, v48
	v_div_scale_f32 v75, s[2:3], v48, v48, v32
	v_rcp_f32_e32 v76, v75
	s_nop 0
	v_fma_f32 v77, -v75, v76, 1.0
	v_fmac_f32_e32 v76, v77, v76
	v_div_scale_f32 v77, vcc, v32, v48, v32
	v_mul_f32_e32 v78, v77, v76
	v_fma_f32 v79, -v75, v78, v77
	v_fmac_f32_e32 v78, v79, v76
	v_fma_f32 v75, -v75, v78, v77
	v_div_fmas_f32 v75, v75, v76, v78
	v_div_fixup_f32 v32, v75, v48, v32
	v_mul_f32_e32 v16, v16, v32
	v_bfe_u32 v32, v16, 16, 1
	v_add3_u32 v16, v16, v32, s15
	global_store_short_d16_hi v[68:69], v16, off offset:2176


; __device__ __forceinline__ float bf2f(unsigned short b) { return __uint_as_float((unsigned)b << 16); }
; __device__ __forceinline__ unsigned f2bf(float f) { unsigned u = __float_as_uint(f); return (u + 0x7fffu + ((u >> 16) & 1u)) >> 16; }
; __device__ __forceinline__ float bf2f(unsigned short b) { return __uint_as_float((unsigned)b << 16); }
; __device__ __forceinline__ unsigned f2bf(float f) { unsigned u = __float_as_uint(f); return (u + 0x7fffu + ((u >> 16) & 1u)) >> 16; }
;     ...
;         for (int d0 = 0; d0 < 4; ++d0) { const float g = bf2f(Gb[(long)orow * ldg + d0 * 32 + r32]); const float sg = g / (1.f + __expf(-g));
;           Yb[(long)orow * ldy + d0 * 32 + r32] = (bf16)f2bf(o[d0][r] * rli * sg); }
	v_lshlrev_b32_e32 v16, 16, v102
	v_mul_f32_e32 v32, 0xbfb8aa3b, v16
	v_exp_f32_e32 v32, v32
	s_nop 0
	v_add_f32_e32 v32, 1.0, v32
	v_div_scale_f32 v48, s[2:3], v32, v32, v16
	v_rcp_f32_e32 v70, v48
	s_nop 0
	v_fma_f32 v71, -v48, v70, 1.0
	v_fmac_f32_e32 v70, v71, v70
	v_div_scale_f32 v71, vcc, v16, v32, v16
	v_mul_f32_e32 v75, v71, v70
	v_fma_f32 v76, -v48, v75, v71
	v_fmac_f32_e32 v75, v76, v70
	v_fma_f32 v48, -v48, v75, v71
	v_div_fmas_f32 v48, v48, v70, v75
	v_div_fixup_f32 v16, v48, v32, v16
	v_mul_f32_e32 v0, v0, v16
	v_bfe_u32 v16, v0, 16, 1
	v_add3_u32 v0, v0, v16, s15
	global_store_short_d16_hi v[68:69], v0, off offset:2240
